# merge gate math via v_rcp/v_exp (f32) + hand-pipelined GLA scan step
# speedup vs baseline: 1.0123x; 1.0123x over previous
.LBB0_118:
	ds_read_b128 v[4:7], v150 offset:32768
	ds_read_b128 v[174:177], v150 offset:34816
	ds_read_b128 v[178:181], v150 offset:36864
	ds_read_b128 v[212:215], v151 offset:49152
	ds_read_b128 v[216:219], v151 offset:51200
	ds_read_b128 v[220:223], v151 offset:53248
	ds_read_b128 v[234:237], v151 offset:55296
	s_waitcnt lgkmcnt(0)
	v_mfma_f32_16x16x32_bf16 v[48:51], v[212:215], v[4:7], v[48:51]
	v_mfma_f32_16x16x32_bf16 v[8:11], v[216:219], v[4:7], v[8:11]
	v_mfma_f32_16x16x32_bf16 v[12:15], v[220:223], v[4:7], v[12:15]
	v_mfma_f32_16x16x32_bf16 v[4:7], v[234:237], v[4:7], v[16:19]
	v_mfma_f32_16x16x32_bf16 v[20:23], v[212:215], v[174:177], v[20:23]
	v_mfma_f32_16x16x32_bf16 v[24:27], v[216:219], v[174:177], v[24:27]
	v_mfma_f32_16x16x32_bf16 v[28:31], v[220:223], v[174:177], v[28:31]
	v_mfma_f32_16x16x32_bf16 v[32:35], v[234:237], v[174:177], v[32:35]
	v_mfma_f32_16x16x32_bf16 v[36:39], v[212:215], v[178:181], v[36:39]
	v_mfma_f32_16x16x32_bf16 v[40:43], v[216:219], v[178:181], v[40:43]
	v_mfma_f32_16x16x32_bf16 v[44:47], v[220:223], v[178:181], v[44:47]
	v_mfma_f32_16x16x32_bf16 v[174:177], v[234:237], v[178:181], v[0:3]
	ds_read_b128 v[16:19], v155 offset:32768
	ds_read_b128 v[178:181], v155 offset:34816
	ds_read_b128 v[212:215], v155 offset:36864
	ds_read_b128 v[216:219], v157 offset:49152
	ds_read_b128 v[220:223], v157 offset:51200
	ds_read_b128 v[234:237], v157 offset:53248
	ds_read_b128 v[238:241], v157 offset:55296
	s_waitcnt lgkmcnt(0)
	v_mfma_f32_16x16x32_bf16 v[0:3], v[216:219], v[16:19], v[48:51]
	s_waitcnt vmcnt(0)
	v_mfma_f32_16x16x32_bf16 v[8:11], v[220:223], v[16:19], v[8:11]
	v_mfma_f32_16x16x32_bf16 v[12:15], v[234:237], v[16:19], v[12:15]
	v_mfma_f32_16x16x32_bf16 v[16:19], v[238:241], v[16:19], v[4:7]
	v_mfma_f32_16x16x32_bf16 v[20:23], v[216:219], v[178:181], v[20:23]
	v_mfma_f32_16x16x32_bf16 v[24:27], v[220:223], v[178:181], v[24:27]
	v_mfma_f32_16x16x32_bf16 v[28:31], v[234:237], v[178:181], v[28:31]
	v_mfma_f32_16x16x32_bf16 v[32:35], v[238:241], v[178:181], v[32:35]
	v_mfma_f32_16x16x32_bf16 v[36:39], v[216:219], v[212:215], v[36:39]
	v_mfma_f32_16x16x32_bf16 v[40:43], v[220:223], v[212:215], v[40:43]
	v_mfma_f32_16x16x32_bf16 v[44:47], v[234:237], v[212:215], v[44:47]
	v_mfma_f32_16x16x32_bf16 v[4:7], v[238:241], v[212:215], v[174:177]
	s_not_b64 s[40:41], s[2:3]
	s_andn2_b64 vcc, exec, s[2:3]
	s_cbranch_vccnz .Lmg_last
	v_lshlrev_b32_e32 v65, 16, v140
	v_and_b32_e32 v67, 0xffff0000, v140
	v_lshlrev_b32_e32 v69, 16, v141
	v_and_b32_e32 v71, 0xffff0000, v141
	v_mul_f32_e32 v65, 0xbfb8aa3b, v65
	v_mul_f32_e32 v67, 0xbfb8aa3b, v67
	v_mul_f32_e32 v69, 0xbfb8aa3b, v69
	v_mul_f32_e32 v71, 0xbfb8aa3b, v71
	v_exp_f32_e32 v65, v65
	v_exp_f32_e32 v67, v67
	v_exp_f32_e32 v69, v69
	v_exp_f32_e32 v71, v71
	v_add_f32_e32 v65, 1.0, v65
	v_add_f32_e32 v67, 1.0, v67
	v_add_f32_e32 v69, 1.0, v69
	v_add_f32_e32 v71, 1.0, v71
	v_rcp_f32_e32 v65, v65
	v_rcp_f32_e32 v67, v67
	v_rcp_f32_e32 v69, v69
	v_rcp_f32_e32 v71, v71
	v_max_f32_e32 v48, 0x358637bd, v65
	v_max_f32_e32 v49, 0x358637bd, v67
	v_max_f32_e32 v50, 0x358637bd, v69
	v_max_f32_e32 v51, 0x358637bd, v71
	v_lshlrev_b32_e32 v65, 16, v102
	v_and_b32_e32 v67, 0xffff0000, v102
	v_lshlrev_b32_e32 v69, 16, v103
	v_and_b32_e32 v71, 0xffff0000, v103
	v_mul_f32_e32 v65, 0xbfb8aa3b, v65
	v_mul_f32_e32 v67, 0xbfb8aa3b, v67
	v_mul_f32_e32 v69, 0xbfb8aa3b, v69
	v_mul_f32_e32 v71, 0xbfb8aa3b, v71
	v_exp_f32_e32 v65, v65
	v_exp_f32_e32 v67, v67
	v_exp_f32_e32 v69, v69
	v_exp_f32_e32 v71, v71
	v_add_f32_e32 v65, 1.0, v65
	v_add_f32_e32 v67, 1.0, v67
	v_add_f32_e32 v69, 1.0, v69
	v_add_f32_e32 v71, 1.0, v71
	v_min_f32_e32 v65, 0x49742400, v65
	v_min_f32_e32 v67, 0x49742400, v67
	v_min_f32_e32 v69, 0x49742400, v69
	v_min_f32_e32 v71, 0x49742400, v71
	v_mul_f32_e32 v48, v48, v65
	v_mul_f32_e32 v49, v49, v67
	v_mul_f32_e32 v50, v50, v69
	v_mul_f32_e32 v51, v51, v71
	v_lshlrev_b32_e32 v65, 16, v106
	v_and_b32_e32 v67, 0xffff0000, v106
	v_lshlrev_b32_e32 v69, 16, v107
	v_and_b32_e32 v71, 0xffff0000, v107
	v_mul_f32_e32 v65, 0xbfb8aa3b, v65
	v_mul_f32_e32 v67, 0xbfb8aa3b, v67
	v_mul_f32_e32 v69, 0xbfb8aa3b, v69
	v_mul_f32_e32 v71, 0xbfb8aa3b, v71
	v_exp_f32_e32 v65, v65
	v_exp_f32_e32 v67, v67
	v_exp_f32_e32 v69, v69
	v_exp_f32_e32 v71, v71
	v_add_f32_e32 v65, 1.0, v65
	v_add_f32_e32 v67, 1.0, v67
	v_add_f32_e32 v69, 1.0, v69
	v_add_f32_e32 v71, 1.0, v71
	v_rcp_f32_e32 v65, v65
	v_rcp_f32_e32 v67, v67
	v_rcp_f32_e32 v69, v69
	v_rcp_f32_e32 v71, v71
	v_max_f32_e32 v102, 0x358637bd, v65
	v_max_f32_e32 v103, 0x358637bd, v67
	v_max_f32_e32 v106, 0x358637bd, v69
	v_max_f32_e32 v107, 0x358637bd, v71
	v_lshlrev_b32_e32 v65, 16, v110
	v_and_b32_e32 v67, 0xffff0000, v110
	v_lshlrev_b32_e32 v69, 16, v111
	v_and_b32_e32 v71, 0xffff0000, v111
	v_mul_f32_e32 v65, 0xbfb8aa3b, v65
	v_mul_f32_e32 v67, 0xbfb8aa3b, v67
	v_mul_f32_e32 v69, 0xbfb8aa3b, v69
	v_mul_f32_e32 v71, 0xbfb8aa3b, v71
	v_exp_f32_e32 v65, v65
	v_exp_f32_e32 v67, v67
	v_exp_f32_e32 v69, v69
	v_exp_f32_e32 v71, v71
	v_add_f32_e32 v65, 1.0, v65
	v_add_f32_e32 v67, 1.0, v67
	v_add_f32_e32 v69, 1.0, v69
	v_add_f32_e32 v71, 1.0, v71
	v_min_f32_e32 v65, 0x49742400, v65
	v_min_f32_e32 v67, 0x49742400, v67
	v_min_f32_e32 v69, 0x49742400, v69
	v_min_f32_e32 v71, 0x49742400, v71
	v_mul_f32_e32 v102, v102, v65
	v_mul_f32_e32 v103, v103, v67
	v_mul_f32_e32 v106, v106, v69
	v_mul_f32_e32 v107, v107, v71
	v_lshlrev_b32_e32 v65, 16, v114
	v_and_b32_e32 v67, 0xffff0000, v114
	v_lshlrev_b32_e32 v69, 16, v115
	v_and_b32_e32 v71, 0xffff0000, v115
	v_mul_f32_e32 v65, 0xbfb8aa3b, v65
	v_mul_f32_e32 v67, 0xbfb8aa3b, v67
	v_mul_f32_e32 v69, 0xbfb8aa3b, v69
	v_mul_f32_e32 v71, 0xbfb8aa3b, v71
	v_exp_f32_e32 v65, v65
	v_exp_f32_e32 v67, v67
	v_exp_f32_e32 v69, v69
	v_exp_f32_e32 v71, v71
	v_add_f32_e32 v65, 1.0, v65
	v_add_f32_e32 v67, 1.0, v67
	v_add_f32_e32 v69, 1.0, v69
	v_add_f32_e32 v71, 1.0, v71
	v_rcp_f32_e32 v65, v65
	v_rcp_f32_e32 v67, v67
	v_rcp_f32_e32 v69, v69
	v_rcp_f32_e32 v71, v71
	v_max_f32_e32 v110, 0x358637bd, v65
	v_max_f32_e32 v111, 0x358637bd, v67
	v_max_f32_e32 v114, 0x358637bd, v69
	v_max_f32_e32 v115, 0x358637bd, v71
	v_lshlrev_b32_e32 v65, 16, v120
	v_and_b32_e32 v67, 0xffff0000, v120
	v_lshlrev_b32_e32 v69, 16, v121
	v_and_b32_e32 v71, 0xffff0000, v121
	v_mul_f32_e32 v65, 0xbfb8aa3b, v65
	v_mul_f32_e32 v67, 0xbfb8aa3b, v67
	v_mul_f32_e32 v69, 0xbfb8aa3b, v69
	v_mul_f32_e32 v71, 0xbfb8aa3b, v71
	v_exp_f32_e32 v65, v65
	v_exp_f32_e32 v67, v67
	v_exp_f32_e32 v69, v69
	v_exp_f32_e32 v71, v71
	v_add_f32_e32 v65, 1.0, v65
	v_add_f32_e32 v67, 1.0, v67
	v_add_f32_e32 v69, 1.0, v69
	v_add_f32_e32 v71, 1.0, v71
	v_min_f32_e32 v65, 0x49742400, v65
	v_min_f32_e32 v67, 0x49742400, v67
	v_min_f32_e32 v69, 0x49742400, v69
	v_min_f32_e32 v71, 0x49742400, v71
	v_mul_f32_e32 v110, v110, v65
	v_mul_f32_e32 v111, v111, v67
	v_mul_f32_e32 v114, v114, v69
	v_mul_f32_e32 v115, v115, v71
	v_lshlrev_b32_e32 v65, 16, v122
	v_and_b32_e32 v67, 0xffff0000, v122
	v_lshlrev_b32_e32 v69, 16, v123
	v_and_b32_e32 v71, 0xffff0000, v123
	v_mul_f32_e32 v65, 0xbfb8aa3b, v65
	v_mul_f32_e32 v67, 0xbfb8aa3b, v67
	v_mul_f32_e32 v69, 0xbfb8aa3b, v69
	v_mul_f32_e32 v71, 0xbfb8aa3b, v71
	v_exp_f32_e32 v65, v65
	v_exp_f32_e32 v67, v67
	v_exp_f32_e32 v69, v69
	v_exp_f32_e32 v71, v71
	v_add_f32_e32 v65, 1.0, v65
	v_add_f32_e32 v67, 1.0, v67
	v_add_f32_e32 v69, 1.0, v69
	v_add_f32_e32 v71, 1.0, v71
	v_rcp_f32_e32 v65, v65
	v_rcp_f32_e32 v67, v67
	v_rcp_f32_e32 v69, v69
	v_rcp_f32_e32 v71, v71
	v_max_f32_e32 v120, 0x358637bd, v65
	v_max_f32_e32 v121, 0x358637bd, v67
	v_max_f32_e32 v122, 0x358637bd, v69
	v_max_f32_e32 v123, 0x358637bd, v71
	v_lshlrev_b32_e32 v65, 16, v128
	v_and_b32_e32 v67, 0xffff0000, v128
	v_lshlrev_b32_e32 v69, 16, v129
	v_and_b32_e32 v71, 0xffff0000, v129
	v_mul_f32_e32 v65, 0xbfb8aa3b, v65
	v_mul_f32_e32 v67, 0xbfb8aa3b, v67
	v_mul_f32_e32 v69, 0xbfb8aa3b, v69
	v_mul_f32_e32 v71, 0xbfb8aa3b, v71
	v_exp_f32_e32 v65, v65
	v_exp_f32_e32 v67, v67
	v_exp_f32_e32 v69, v69
	v_exp_f32_e32 v71, v71
	v_add_f32_e32 v65, 1.0, v65
	v_add_f32_e32 v67, 1.0, v67
	v_add_f32_e32 v69, 1.0, v69
	v_add_f32_e32 v71, 1.0, v71
	v_min_f32_e32 v65, 0x49742400, v65
	v_min_f32_e32 v67, 0x49742400, v67
	v_min_f32_e32 v69, 0x49742400, v69
	v_min_f32_e32 v71, 0x49742400, v71
	v_mul_f32_e32 v120, v120, v65
	v_mul_f32_e32 v121, v121, v67
	v_mul_f32_e32 v122, v122, v69
	v_mul_f32_e32 v123, v123, v71
	v_lshlrev_b32_e32 v65, 16, v130
	v_and_b32_e32 v67, 0xffff0000, v130
	v_lshlrev_b32_e32 v69, 16, v131
	v_and_b32_e32 v71, 0xffff0000, v131
	v_mul_f32_e32 v65, 0xbfb8aa3b, v65
	v_mul_f32_e32 v67, 0xbfb8aa3b, v67
	v_mul_f32_e32 v69, 0xbfb8aa3b, v69
	v_mul_f32_e32 v71, 0xbfb8aa3b, v71
	v_exp_f32_e32 v65, v65
	v_exp_f32_e32 v67, v67
	v_exp_f32_e32 v69, v69
	v_exp_f32_e32 v71, v71
	v_add_f32_e32 v65, 1.0, v65
	v_add_f32_e32 v67, 1.0, v67
	v_add_f32_e32 v69, 1.0, v69
	v_add_f32_e32 v71, 1.0, v71
	v_rcp_f32_e32 v65, v65
	v_rcp_f32_e32 v67, v67
	v_rcp_f32_e32 v69, v69
	v_rcp_f32_e32 v71, v71
	v_max_f32_e32 v128, 0x358637bd, v65
	v_max_f32_e32 v129, 0x358637bd, v67
	v_max_f32_e32 v130, 0x358637bd, v69
	v_max_f32_e32 v131, 0x358637bd, v71
	v_lshlrev_b32_e32 v65, 16, v136
	v_and_b32_e32 v67, 0xffff0000, v136
	v_lshlrev_b32_e32 v69, 16, v137
	v_and_b32_e32 v71, 0xffff0000, v137
	v_mul_f32_e32 v65, 0xbfb8aa3b, v65
	v_mul_f32_e32 v67, 0xbfb8aa3b, v67
	v_mul_f32_e32 v69, 0xbfb8aa3b, v69
	v_mul_f32_e32 v71, 0xbfb8aa3b, v71
	v_exp_f32_e32 v65, v65
	v_exp_f32_e32 v67, v67
	v_exp_f32_e32 v69, v69
	v_exp_f32_e32 v71, v71
	v_add_f32_e32 v65, 1.0, v65
	v_add_f32_e32 v67, 1.0, v67
	v_add_f32_e32 v69, 1.0, v69
	v_add_f32_e32 v71, 1.0, v71
	v_min_f32_e32 v65, 0x49742400, v65
	v_min_f32_e32 v67, 0x49742400, v67
	v_min_f32_e32 v69, 0x49742400, v69
	v_min_f32_e32 v71, 0x49742400, v71
	v_mul_f32_e32 v128, v128, v65
	v_mul_f32_e32 v129, v129, v67
	v_mul_f32_e32 v130, v130, v69
	v_mul_f32_e32 v131, v131, v71
	v_lshlrev_b32_e32 v65, 16, v138
	v_and_b32_e32 v67, 0xffff0000, v138
	v_lshlrev_b32_e32 v69, 16, v139
	v_and_b32_e32 v71, 0xffff0000, v139
	v_mul_f32_e32 v65, 0xbfb8aa3b, v65
	v_mul_f32_e32 v67, 0xbfb8aa3b, v67
	v_mul_f32_e32 v69, 0xbfb8aa3b, v69
	v_mul_f32_e32 v71, 0xbfb8aa3b, v71
	v_exp_f32_e32 v65, v65
	v_exp_f32_e32 v67, v67
	v_exp_f32_e32 v69, v69
	v_exp_f32_e32 v71, v71
	v_add_f32_e32 v65, 1.0, v65
	v_add_f32_e32 v67, 1.0, v67
	v_add_f32_e32 v69, 1.0, v69
	v_add_f32_e32 v71, 1.0, v71
	v_rcp_f32_e32 v65, v65
	v_rcp_f32_e32 v67, v67
	v_rcp_f32_e32 v69, v69
	v_rcp_f32_e32 v71, v71
	v_max_f32_e32 v136, 0x358637bd, v65
	v_max_f32_e32 v137, 0x358637bd, v67
	v_max_f32_e32 v138, 0x358637bd, v69
	v_max_f32_e32 v139, 0x358637bd, v71
	v_lshlrev_b32_e32 v65, 16, v134
	v_and_b32_e32 v67, 0xffff0000, v134
	v_lshlrev_b32_e32 v69, 16, v135
	v_and_b32_e32 v71, 0xffff0000, v135
	v_mul_f32_e32 v65, 0xbfb8aa3b, v65
	v_mul_f32_e32 v67, 0xbfb8aa3b, v67
	v_mul_f32_e32 v69, 0xbfb8aa3b, v69
	v_mul_f32_e32 v71, 0xbfb8aa3b, v71
	v_exp_f32_e32 v65, v65
	v_exp_f32_e32 v67, v67
	v_exp_f32_e32 v69, v69
	v_exp_f32_e32 v71, v71
	v_add_f32_e32 v65, 1.0, v65
	v_add_f32_e32 v67, 1.0, v67
	v_add_f32_e32 v69, 1.0, v69
	v_add_f32_e32 v71, 1.0, v71
	v_min_f32_e32 v65, 0x49742400, v65
	v_min_f32_e32 v67, 0x49742400, v67
	v_min_f32_e32 v69, 0x49742400, v69
	v_min_f32_e32 v71, 0x49742400, v71
	v_mul_f32_e32 v136, v136, v65
	v_mul_f32_e32 v137, v137, v67
	v_mul_f32_e32 v138, v138, v69
	v_mul_f32_e32 v139, v139, v71
	v_lshlrev_b32_e32 v65, 16, v132
	v_and_b32_e32 v67, 0xffff0000, v132
	v_lshlrev_b32_e32 v69, 16, v133
	v_and_b32_e32 v71, 0xffff0000, v133
	v_mul_f32_e32 v65, 0xbfb8aa3b, v65
	v_mul_f32_e32 v67, 0xbfb8aa3b, v67
	v_mul_f32_e32 v69, 0xbfb8aa3b, v69
	v_mul_f32_e32 v71, 0xbfb8aa3b, v71
	v_exp_f32_e32 v65, v65
	v_exp_f32_e32 v67, v67
	v_exp_f32_e32 v69, v69
	v_exp_f32_e32 v71, v71
	v_add_f32_e32 v65, 1.0, v65
	v_add_f32_e32 v67, 1.0, v67
	v_add_f32_e32 v69, 1.0, v69
	v_add_f32_e32 v71, 1.0, v71
	v_rcp_f32_e32 v65, v65
	v_rcp_f32_e32 v67, v67
	v_rcp_f32_e32 v69, v69
	v_rcp_f32_e32 v71, v71
	v_max_f32_e32 v134, 0x358637bd, v65
	v_max_f32_e32 v135, 0x358637bd, v67
	v_max_f32_e32 v132, 0x358637bd, v69
	v_max_f32_e32 v133, 0x358637bd, v71
	v_lshlrev_b32_e32 v65, 16, v126
	v_and_b32_e32 v67, 0xffff0000, v126
	v_lshlrev_b32_e32 v69, 16, v127
	v_and_b32_e32 v71, 0xffff0000, v127
	v_mul_f32_e32 v65, 0xbfb8aa3b, v65
	v_mul_f32_e32 v67, 0xbfb8aa3b, v67
	v_mul_f32_e32 v69, 0xbfb8aa3b, v69
	v_mul_f32_e32 v71, 0xbfb8aa3b, v71
	v_exp_f32_e32 v65, v65
	v_exp_f32_e32 v67, v67
	v_exp_f32_e32 v69, v69
	v_exp_f32_e32 v71, v71
	v_add_f32_e32 v65, 1.0, v65
	v_add_f32_e32 v67, 1.0, v67
	v_add_f32_e32 v69, 1.0, v69
	v_add_f32_e32 v71, 1.0, v71
	v_min_f32_e32 v65, 0x49742400, v65
	v_min_f32_e32 v67, 0x49742400, v67
	v_min_f32_e32 v69, 0x49742400, v69
	v_min_f32_e32 v71, 0x49742400, v71
	v_mul_f32_e32 v134, v134, v65
	v_mul_f32_e32 v135, v135, v67
	v_mul_f32_e32 v132, v132, v69
	v_mul_f32_e32 v133, v133, v71
	v_lshlrev_b32_e32 v65, 16, v124
	v_and_b32_e32 v67, 0xffff0000, v124
	v_lshlrev_b32_e32 v69, 16, v125
	v_and_b32_e32 v71, 0xffff0000, v125
	v_mul_f32_e32 v65, 0xbfb8aa3b, v65
	v_mul_f32_e32 v67, 0xbfb8aa3b, v67
	v_mul_f32_e32 v69, 0xbfb8aa3b, v69
	v_mul_f32_e32 v71, 0xbfb8aa3b, v71
	v_exp_f32_e32 v65, v65
	v_exp_f32_e32 v67, v67
	v_exp_f32_e32 v69, v69
	v_exp_f32_e32 v71, v71
	v_add_f32_e32 v65, 1.0, v65
	v_add_f32_e32 v67, 1.0, v67
	v_add_f32_e32 v69, 1.0, v69
	v_add_f32_e32 v71, 1.0, v71
	v_rcp_f32_e32 v65, v65
	v_rcp_f32_e32 v67, v67
	v_rcp_f32_e32 v69, v69
	v_rcp_f32_e32 v71, v71
	v_max_f32_e32 v126, 0x358637bd, v65
	v_max_f32_e32 v127, 0x358637bd, v67
	v_max_f32_e32 v124, 0x358637bd, v69
	v_max_f32_e32 v125, 0x358637bd, v71
	v_lshlrev_b32_e32 v65, 16, v118
	v_and_b32_e32 v67, 0xffff0000, v118
	v_lshlrev_b32_e32 v69, 16, v119
	v_and_b32_e32 v71, 0xffff0000, v119
	v_mul_f32_e32 v65, 0xbfb8aa3b, v65
	v_mul_f32_e32 v67, 0xbfb8aa3b, v67
	v_mul_f32_e32 v69, 0xbfb8aa3b, v69
	v_mul_f32_e32 v71, 0xbfb8aa3b, v71
	v_exp_f32_e32 v65, v65
	v_exp_f32_e32 v67, v67
	v_exp_f32_e32 v69, v69
	v_exp_f32_e32 v71, v71
	v_add_f32_e32 v65, 1.0, v65
	v_add_f32_e32 v67, 1.0, v67
	v_add_f32_e32 v69, 1.0, v69
	v_add_f32_e32 v71, 1.0, v71
	v_min_f32_e32 v65, 0x49742400, v65
	v_min_f32_e32 v67, 0x49742400, v67
	v_min_f32_e32 v69, 0x49742400, v69
	v_min_f32_e32 v71, 0x49742400, v71
	v_mul_f32_e32 v126, v126, v65
	v_mul_f32_e32 v127, v127, v67
	v_mul_f32_e32 v124, v124, v69
	v_mul_f32_e32 v125, v125, v71
	v_lshlrev_b32_e32 v65, 16, v116
	v_and_b32_e32 v67, 0xffff0000, v116
	v_lshlrev_b32_e32 v69, 16, v117
	v_and_b32_e32 v71, 0xffff0000, v117
	v_mul_f32_e32 v65, 0xbfb8aa3b, v65
	v_mul_f32_e32 v67, 0xbfb8aa3b, v67
	v_mul_f32_e32 v69, 0xbfb8aa3b, v69
	v_mul_f32_e32 v71, 0xbfb8aa3b, v71
	v_exp_f32_e32 v65, v65
	v_exp_f32_e32 v67, v67
	v_exp_f32_e32 v69, v69
	v_exp_f32_e32 v71, v71
	v_add_f32_e32 v65, 1.0, v65
	v_add_f32_e32 v67, 1.0, v67
	v_add_f32_e32 v69, 1.0, v69
	v_add_f32_e32 v71, 1.0, v71
	v_rcp_f32_e32 v65, v65
	v_rcp_f32_e32 v67, v67
	v_rcp_f32_e32 v69, v69
	v_rcp_f32_e32 v71, v71
	v_max_f32_e32 v118, 0x358637bd, v65
	v_max_f32_e32 v119, 0x358637bd, v67
	v_max_f32_e32 v116, 0x358637bd, v69
	v_max_f32_e32 v117, 0x358637bd, v71
	v_lshlrev_b32_e32 v65, 16, v112
	v_and_b32_e32 v67, 0xffff0000, v112
	v_lshlrev_b32_e32 v69, 16, v113
	v_and_b32_e32 v71, 0xffff0000, v113
	v_mul_f32_e32 v65, 0xbfb8aa3b, v65
	v_mul_f32_e32 v67, 0xbfb8aa3b, v67
	v_mul_f32_e32 v69, 0xbfb8aa3b, v69
	v_mul_f32_e32 v71, 0xbfb8aa3b, v71
	v_exp_f32_e32 v65, v65
	v_exp_f32_e32 v67, v67
	v_exp_f32_e32 v69, v69
	v_exp_f32_e32 v71, v71
	v_add_f32_e32 v65, 1.0, v65
	v_add_f32_e32 v67, 1.0, v67
	v_add_f32_e32 v69, 1.0, v69
	v_add_f32_e32 v71, 1.0, v71
	v_min_f32_e32 v65, 0x49742400, v65
	v_min_f32_e32 v67, 0x49742400, v67
	v_min_f32_e32 v69, 0x49742400, v69
	v_min_f32_e32 v71, 0x49742400, v71
	v_mul_f32_e32 v118, v118, v65
	v_mul_f32_e32 v119, v119, v67
	v_mul_f32_e32 v116, v116, v69
	v_mul_f32_e32 v117, v117, v71
	v_lshlrev_b32_e32 v65, 16, v108
	v_and_b32_e32 v67, 0xffff0000, v108
	v_lshlrev_b32_e32 v69, 16, v109
	v_and_b32_e32 v71, 0xffff0000, v109
	v_mul_f32_e32 v65, 0xbfb8aa3b, v65
	v_mul_f32_e32 v67, 0xbfb8aa3b, v67
	v_mul_f32_e32 v69, 0xbfb8aa3b, v69
	v_mul_f32_e32 v71, 0xbfb8aa3b, v71
	v_exp_f32_e32 v65, v65
	v_exp_f32_e32 v67, v67
	v_exp_f32_e32 v69, v69
	v_exp_f32_e32 v71, v71
	v_add_f32_e32 v65, 1.0, v65
	v_add_f32_e32 v67, 1.0, v67
	v_add_f32_e32 v69, 1.0, v69
	v_add_f32_e32 v71, 1.0, v71
	v_rcp_f32_e32 v65, v65
	v_rcp_f32_e32 v67, v67
	v_rcp_f32_e32 v69, v69
	v_rcp_f32_e32 v71, v71
	v_max_f32_e32 v112, 0x358637bd, v65
	v_max_f32_e32 v113, 0x358637bd, v67
	v_max_f32_e32 v108, 0x358637bd, v69
	v_max_f32_e32 v109, 0x358637bd, v71
	v_lshlrev_b32_e32 v65, 16, v104
	v_and_b32_e32 v67, 0xffff0000, v104
	v_lshlrev_b32_e32 v69, 16, v105
	v_and_b32_e32 v71, 0xffff0000, v105
	v_mul_f32_e32 v65, 0xbfb8aa3b, v65
	v_mul_f32_e32 v67, 0xbfb8aa3b, v67
	v_mul_f32_e32 v69, 0xbfb8aa3b, v69
	v_mul_f32_e32 v71, 0xbfb8aa3b, v71
	v_exp_f32_e32 v65, v65
	v_exp_f32_e32 v67, v67
	v_exp_f32_e32 v69, v69
	v_exp_f32_e32 v71, v71
	v_add_f32_e32 v65, 1.0, v65
	v_add_f32_e32 v67, 1.0, v67
	v_add_f32_e32 v69, 1.0, v69
	v_add_f32_e32 v71, 1.0, v71
	v_min_f32_e32 v65, 0x49742400, v65
	v_min_f32_e32 v67, 0x49742400, v67
	v_min_f32_e32 v69, 0x49742400, v69
	v_min_f32_e32 v71, 0x49742400, v71
	v_mul_f32_e32 v112, v112, v65
	v_mul_f32_e32 v113, v113, v67
	v_mul_f32_e32 v108, v108, v69
	v_mul_f32_e32 v109, v109, v71
	v_lshlrev_b32_e32 v65, 16, v100
	v_and_b32_e32 v67, 0xffff0000, v100
	v_lshlrev_b32_e32 v69, 16, v101
	v_and_b32_e32 v71, 0xffff0000, v101
	v_mul_f32_e32 v65, 0xbfb8aa3b, v65
	v_mul_f32_e32 v67, 0xbfb8aa3b, v67
	v_mul_f32_e32 v69, 0xbfb8aa3b, v69
	v_mul_f32_e32 v71, 0xbfb8aa3b, v71
	v_exp_f32_e32 v65, v65
	v_exp_f32_e32 v67, v67
	v_exp_f32_e32 v69, v69
	v_exp_f32_e32 v71, v71
	v_add_f32_e32 v65, 1.0, v65
	v_add_f32_e32 v67, 1.0, v67
	v_add_f32_e32 v69, 1.0, v69
	v_add_f32_e32 v71, 1.0, v71
	v_rcp_f32_e32 v65, v65
	v_rcp_f32_e32 v67, v67
	v_rcp_f32_e32 v69, v69
	v_rcp_f32_e32 v71, v71
	v_max_f32_e32 v104, 0x358637bd, v65
	v_max_f32_e32 v105, 0x358637bd, v67
	v_max_f32_e32 v100, 0x358637bd, v69
	v_max_f32_e32 v101, 0x358637bd, v71
	v_lshlrev_b32_e32 v65, 16, v98
	v_and_b32_e32 v67, 0xffff0000, v98
	v_lshlrev_b32_e32 v69, 16, v99
	v_and_b32_e32 v71, 0xffff0000, v99
	v_mul_f32_e32 v65, 0xbfb8aa3b, v65
	v_mul_f32_e32 v67, 0xbfb8aa3b, v67
	v_mul_f32_e32 v69, 0xbfb8aa3b, v69
	v_mul_f32_e32 v71, 0xbfb8aa3b, v71
	v_exp_f32_e32 v65, v65
	v_exp_f32_e32 v67, v67
	v_exp_f32_e32 v69, v69
	v_exp_f32_e32 v71, v71
	v_add_f32_e32 v65, 1.0, v65
	v_add_f32_e32 v67, 1.0, v67
	v_add_f32_e32 v69, 1.0, v69
	v_add_f32_e32 v71, 1.0, v71
	v_min_f32_e32 v65, 0x49742400, v65
	v_min_f32_e32 v67, 0x49742400, v67
	v_min_f32_e32 v69, 0x49742400, v69
	v_min_f32_e32 v71, 0x49742400, v71
	v_mul_f32_e32 v104, v104, v65
	v_mul_f32_e32 v105, v105, v67
	v_mul_f32_e32 v100, v100, v69
	v_mul_f32_e32 v101, v101, v71
	v_lshlrev_b32_e32 v65, 16, v96
	v_and_b32_e32 v67, 0xffff0000, v96
	v_lshlrev_b32_e32 v69, 16, v97
	v_and_b32_e32 v71, 0xffff0000, v97
	v_mul_f32_e32 v65, 0xbfb8aa3b, v65
	v_mul_f32_e32 v67, 0xbfb8aa3b, v67
	v_mul_f32_e32 v69, 0xbfb8aa3b, v69
	v_mul_f32_e32 v71, 0xbfb8aa3b, v71
	v_exp_f32_e32 v65, v65
	v_exp_f32_e32 v67, v67
	v_exp_f32_e32 v69, v69
	v_exp_f32_e32 v71, v71
	v_add_f32_e32 v65, 1.0, v65
	v_add_f32_e32 v67, 1.0, v67
	v_add_f32_e32 v69, 1.0, v69
	v_add_f32_e32 v71, 1.0, v71
	v_rcp_f32_e32 v65, v65
	v_rcp_f32_e32 v67, v67
	v_rcp_f32_e32 v69, v69
	v_rcp_f32_e32 v71, v71
	v_max_f32_e32 v98, 0x358637bd, v65
	v_max_f32_e32 v99, 0x358637bd, v67
	v_max_f32_e32 v96, 0x358637bd, v69
	v_max_f32_e32 v97, 0x358637bd, v71
	v_lshlrev_b32_e32 v65, 16, v94
	v_and_b32_e32 v67, 0xffff0000, v94
	v_lshlrev_b32_e32 v69, 16, v95
	v_and_b32_e32 v71, 0xffff0000, v95
	v_mul_f32_e32 v65, 0xbfb8aa3b, v65
	v_mul_f32_e32 v67, 0xbfb8aa3b, v67
	v_mul_f32_e32 v69, 0xbfb8aa3b, v69
	v_mul_f32_e32 v71, 0xbfb8aa3b, v71
	v_exp_f32_e32 v65, v65
	v_exp_f32_e32 v67, v67
	v_exp_f32_e32 v69, v69
	v_exp_f32_e32 v71, v71
	v_add_f32_e32 v65, 1.0, v65
	v_add_f32_e32 v67, 1.0, v67
	v_add_f32_e32 v69, 1.0, v69
	v_add_f32_e32 v71, 1.0, v71
	v_min_f32_e32 v65, 0x49742400, v65
	v_min_f32_e32 v67, 0x49742400, v67
	v_min_f32_e32 v69, 0x49742400, v69
	v_min_f32_e32 v71, 0x49742400, v71
	v_mul_f32_e32 v98, v98, v65
	v_mul_f32_e32 v99, v99, v67
	v_mul_f32_e32 v96, v96, v69
	v_mul_f32_e32 v97, v97, v71
	s_branch .LBB0_111
.Lmg_last:
	v_lshlrev_b32_e32 v65, 16, v140
	v_and_b32_e32 v67, 0xffff0000, v140
	v_lshlrev_b32_e32 v69, 16, v141
	v_and_b32_e32 v71, 0xffff0000, v141
	v_mul_f32_e32 v65, 0xbfb8aa3b, v65
	v_mul_f32_e32 v67, 0xbfb8aa3b, v67
	v_mul_f32_e32 v69, 0xbfb8aa3b, v69
	v_mul_f32_e32 v71, 0xbfb8aa3b, v71
	v_exp_f32_e32 v65, v65
	v_exp_f32_e32 v67, v67
	v_exp_f32_e32 v69, v69
	v_exp_f32_e32 v71, v71
	v_add_f32_e32 v65, 1.0, v65
	v_add_f32_e32 v67, 1.0, v67
	v_add_f32_e32 v69, 1.0, v69
	v_add_f32_e32 v71, 1.0, v71
	v_rcp_f32_e32 v65, v65
	v_rcp_f32_e32 v67, v67
	v_rcp_f32_e32 v69, v69
	v_rcp_f32_e32 v71, v71
	v_max_f32_e32 v48, 0x358637bd, v65
	v_max_f32_e32 v49, 0x358637bd, v67
	v_max_f32_e32 v50, 0x358637bd, v69
	v_max_f32_e32 v51, 0x358637bd, v71
	v_lshlrev_b32_e32 v65, 16, v106
	v_and_b32_e32 v67, 0xffff0000, v106
	v_lshlrev_b32_e32 v69, 16, v107
	v_and_b32_e32 v71, 0xffff0000, v107
	v_mul_f32_e32 v65, 0xbfb8aa3b, v65
	v_mul_f32_e32 v67, 0xbfb8aa3b, v67
	v_mul_f32_e32 v69, 0xbfb8aa3b, v69
	v_mul_f32_e32 v71, 0xbfb8aa3b, v71
	v_exp_f32_e32 v65, v65
	v_exp_f32_e32 v67, v67
	v_exp_f32_e32 v69, v69
	v_exp_f32_e32 v71, v71
	v_add_f32_e32 v65, 1.0, v65
	v_add_f32_e32 v67, 1.0, v67
	v_add_f32_e32 v69, 1.0, v69
	v_add_f32_e32 v71, 1.0, v71
	v_rcp_f32_e32 v65, v65
	v_rcp_f32_e32 v67, v67
	v_rcp_f32_e32 v69, v69
	v_rcp_f32_e32 v71, v71
	v_max_f32_e32 v102, 0x358637bd, v65
	v_max_f32_e32 v103, 0x358637bd, v67
	v_max_f32_e32 v106, 0x358637bd, v69
	v_max_f32_e32 v107, 0x358637bd, v71
	v_lshlrev_b32_e32 v65, 16, v114
	v_and_b32_e32 v67, 0xffff0000, v114
	v_lshlrev_b32_e32 v69, 16, v115
	v_and_b32_e32 v71, 0xffff0000, v115
	v_mul_f32_e32 v65, 0xbfb8aa3b, v65
	v_mul_f32_e32 v67, 0xbfb8aa3b, v67
	v_mul_f32_e32 v69, 0xbfb8aa3b, v69
	v_mul_f32_e32 v71, 0xbfb8aa3b, v71
	v_exp_f32_e32 v65, v65
	v_exp_f32_e32 v67, v67
	v_exp_f32_e32 v69, v69
	v_exp_f32_e32 v71, v71
	v_add_f32_e32 v65, 1.0, v65
	v_add_f32_e32 v67, 1.0, v67
	v_add_f32_e32 v69, 1.0, v69
	v_add_f32_e32 v71, 1.0, v71
	v_rcp_f32_e32 v65, v65
	v_rcp_f32_e32 v67, v67
	v_rcp_f32_e32 v69, v69
	v_rcp_f32_e32 v71, v71
	v_max_f32_e32 v110, 0x358637bd, v65
	v_max_f32_e32 v111, 0x358637bd, v67
	v_max_f32_e32 v114, 0x358637bd, v69
	v_max_f32_e32 v115, 0x358637bd, v71
	v_lshlrev_b32_e32 v65, 16, v122
	v_and_b32_e32 v67, 0xffff0000, v122
	v_lshlrev_b32_e32 v69, 16, v123
	v_and_b32_e32 v71, 0xffff0000, v123
	v_mul_f32_e32 v65, 0xbfb8aa3b, v65
	v_mul_f32_e32 v67, 0xbfb8aa3b, v67
	v_mul_f32_e32 v69, 0xbfb8aa3b, v69
	v_mul_f32_e32 v71, 0xbfb8aa3b, v71
	v_exp_f32_e32 v65, v65
	v_exp_f32_e32 v67, v67
	v_exp_f32_e32 v69, v69
	v_exp_f32_e32 v71, v71
	v_add_f32_e32 v65, 1.0, v65
	v_add_f32_e32 v67, 1.0, v67
	v_add_f32_e32 v69, 1.0, v69
	v_add_f32_e32 v71, 1.0, v71
	v_rcp_f32_e32 v65, v65
	v_rcp_f32_e32 v67, v67
	v_rcp_f32_e32 v69, v69
	v_rcp_f32_e32 v71, v71
	v_max_f32_e32 v120, 0x358637bd, v65
	v_max_f32_e32 v121, 0x358637bd, v67
	v_max_f32_e32 v122, 0x358637bd, v69
	v_max_f32_e32 v123, 0x358637bd, v71
	v_lshlrev_b32_e32 v65, 16, v130
	v_and_b32_e32 v67, 0xffff0000, v130
	v_lshlrev_b32_e32 v69, 16, v131
	v_and_b32_e32 v71, 0xffff0000, v131
	v_mul_f32_e32 v65, 0xbfb8aa3b, v65
	v_mul_f32_e32 v67, 0xbfb8aa3b, v67
	v_mul_f32_e32 v69, 0xbfb8aa3b, v69
	v_mul_f32_e32 v71, 0xbfb8aa3b, v71
	v_exp_f32_e32 v65, v65
	v_exp_f32_e32 v67, v67
	v_exp_f32_e32 v69, v69
	v_exp_f32_e32 v71, v71
	v_add_f32_e32 v65, 1.0, v65
	v_add_f32_e32 v67, 1.0, v67
	v_add_f32_e32 v69, 1.0, v69
	v_add_f32_e32 v71, 1.0, v71
	v_rcp_f32_e32 v65, v65
	v_rcp_f32_e32 v67, v67
	v_rcp_f32_e32 v69, v69
	v_rcp_f32_e32 v71, v71
	v_max_f32_e32 v128, 0x358637bd, v65
	v_max_f32_e32 v129, 0x358637bd, v67
	v_max_f32_e32 v130, 0x358637bd, v69
	v_max_f32_e32 v131, 0x358637bd, v71
	v_lshlrev_b32_e32 v65, 16, v138
	v_and_b32_e32 v67, 0xffff0000, v138
	v_lshlrev_b32_e32 v69, 16, v139
	v_and_b32_e32 v71, 0xffff0000, v139
	v_mul_f32_e32 v65, 0xbfb8aa3b, v65
	v_mul_f32_e32 v67, 0xbfb8aa3b, v67
	v_mul_f32_e32 v69, 0xbfb8aa3b, v69
	v_mul_f32_e32 v71, 0xbfb8aa3b, v71
	v_exp_f32_e32 v65, v65
	v_exp_f32_e32 v67, v67
	v_exp_f32_e32 v69, v69
	v_exp_f32_e32 v71, v71
	v_add_f32_e32 v65, 1.0, v65
	v_add_f32_e32 v67, 1.0, v67
	v_add_f32_e32 v69, 1.0, v69
	v_add_f32_e32 v71, 1.0, v71
	v_rcp_f32_e32 v65, v65
	v_rcp_f32_e32 v67, v67
	v_rcp_f32_e32 v69, v69
	v_rcp_f32_e32 v71, v71
	v_max_f32_e32 v136, 0x358637bd, v65
	v_max_f32_e32 v137, 0x358637bd, v67
	v_max_f32_e32 v138, 0x358637bd, v69
	v_max_f32_e32 v139, 0x358637bd, v71
	v_lshlrev_b32_e32 v65, 16, v132
	v_and_b32_e32 v67, 0xffff0000, v132
	v_lshlrev_b32_e32 v69, 16, v133
	v_and_b32_e32 v71, 0xffff0000, v133
	v_mul_f32_e32 v65, 0xbfb8aa3b, v65
	v_mul_f32_e32 v67, 0xbfb8aa3b, v67
	v_mul_f32_e32 v69, 0xbfb8aa3b, v69
	v_mul_f32_e32 v71, 0xbfb8aa3b, v71
	v_exp_f32_e32 v65, v65
	v_exp_f32_e32 v67, v67
	v_exp_f32_e32 v69, v69
	v_exp_f32_e32 v71, v71
	v_add_f32_e32 v65, 1.0, v65
	v_add_f32_e32 v67, 1.0, v67
	v_add_f32_e32 v69, 1.0, v69
	v_add_f32_e32 v71, 1.0, v71
	v_rcp_f32_e32 v65, v65
	v_rcp_f32_e32 v67, v67
	v_rcp_f32_e32 v69, v69
	v_rcp_f32_e32 v71, v71
	v_max_f32_e32 v134, 0x358637bd, v65
	v_max_f32_e32 v135, 0x358637bd, v67
	v_max_f32_e32 v132, 0x358637bd, v69
	v_max_f32_e32 v133, 0x358637bd, v71
	v_lshlrev_b32_e32 v65, 16, v124
	v_and_b32_e32 v67, 0xffff0000, v124
	v_lshlrev_b32_e32 v69, 16, v125
	v_and_b32_e32 v71, 0xffff0000, v125
	v_mul_f32_e32 v65, 0xbfb8aa3b, v65
	v_mul_f32_e32 v67, 0xbfb8aa3b, v67
	v_mul_f32_e32 v69, 0xbfb8aa3b, v69
	v_mul_f32_e32 v71, 0xbfb8aa3b, v71
	v_exp_f32_e32 v65, v65
	v_exp_f32_e32 v67, v67
	v_exp_f32_e32 v69, v69
	v_exp_f32_e32 v71, v71
	v_add_f32_e32 v65, 1.0, v65
	v_add_f32_e32 v67, 1.0, v67
	v_add_f32_e32 v69, 1.0, v69
	v_add_f32_e32 v71, 1.0, v71
	v_rcp_f32_e32 v65, v65
	v_rcp_f32_e32 v67, v67
	v_rcp_f32_e32 v69, v69
	v_rcp_f32_e32 v71, v71
	v_max_f32_e32 v126, 0x358637bd, v65
	v_max_f32_e32 v127, 0x358637bd, v67
	v_max_f32_e32 v124, 0x358637bd, v69
	v_max_f32_e32 v125, 0x358637bd, v71
	v_lshlrev_b32_e32 v65, 16, v116
	v_and_b32_e32 v67, 0xffff0000, v116
	v_lshlrev_b32_e32 v69, 16, v117
	v_and_b32_e32 v71, 0xffff0000, v117
	v_mul_f32_e32 v65, 0xbfb8aa3b, v65
	v_mul_f32_e32 v67, 0xbfb8aa3b, v67
	v_mul_f32_e32 v69, 0xbfb8aa3b, v69
	v_mul_f32_e32 v71, 0xbfb8aa3b, v71
	v_exp_f32_e32 v65, v65
	v_exp_f32_e32 v67, v67
	v_exp_f32_e32 v69, v69
	v_exp_f32_e32 v71, v71
	v_add_f32_e32 v65, 1.0, v65
	v_add_f32_e32 v67, 1.0, v67
	v_add_f32_e32 v69, 1.0, v69
	v_add_f32_e32 v71, 1.0, v71
	v_rcp_f32_e32 v65, v65
	v_rcp_f32_e32 v67, v67
	v_rcp_f32_e32 v69, v69
	v_rcp_f32_e32 v71, v71
	v_max_f32_e32 v118, 0x358637bd, v65
	v_max_f32_e32 v119, 0x358637bd, v67
	v_max_f32_e32 v116, 0x358637bd, v69
	v_max_f32_e32 v117, 0x358637bd, v71
	v_lshlrev_b32_e32 v65, 16, v108
	v_and_b32_e32 v67, 0xffff0000, v108
	v_lshlrev_b32_e32 v69, 16, v109
	v_and_b32_e32 v71, 0xffff0000, v109
	v_mul_f32_e32 v65, 0xbfb8aa3b, v65
	v_mul_f32_e32 v67, 0xbfb8aa3b, v67
	v_mul_f32_e32 v69, 0xbfb8aa3b, v69
	v_mul_f32_e32 v71, 0xbfb8aa3b, v71
	v_exp_f32_e32 v65, v65
	v_exp_f32_e32 v67, v67
	v_exp_f32_e32 v69, v69
	v_exp_f32_e32 v71, v71
	v_add_f32_e32 v65, 1.0, v65
	v_add_f32_e32 v67, 1.0, v67
	v_add_f32_e32 v69, 1.0, v69
	v_add_f32_e32 v71, 1.0, v71
	v_rcp_f32_e32 v65, v65
	v_rcp_f32_e32 v67, v67
	v_rcp_f32_e32 v69, v69
	v_rcp_f32_e32 v71, v71
	v_max_f32_e32 v112, 0x358637bd, v65
	v_max_f32_e32 v113, 0x358637bd, v67
	v_max_f32_e32 v108, 0x358637bd, v69
	v_max_f32_e32 v109, 0x358637bd, v71
	v_lshlrev_b32_e32 v65, 16, v100
	v_and_b32_e32 v67, 0xffff0000, v100
	v_lshlrev_b32_e32 v69, 16, v101
	v_and_b32_e32 v71, 0xffff0000, v101
	v_mul_f32_e32 v65, 0xbfb8aa3b, v65
	v_mul_f32_e32 v67, 0xbfb8aa3b, v67
	v_mul_f32_e32 v69, 0xbfb8aa3b, v69
	v_mul_f32_e32 v71, 0xbfb8aa3b, v71
	v_exp_f32_e32 v65, v65
	v_exp_f32_e32 v67, v67
	v_exp_f32_e32 v69, v69
	v_exp_f32_e32 v71, v71
	v_add_f32_e32 v65, 1.0, v65
	v_add_f32_e32 v67, 1.0, v67
	v_add_f32_e32 v69, 1.0, v69
	v_add_f32_e32 v71, 1.0, v71
	v_rcp_f32_e32 v65, v65
	v_rcp_f32_e32 v67, v67
	v_rcp_f32_e32 v69, v69
	v_rcp_f32_e32 v71, v71
	v_max_f32_e32 v104, 0x358637bd, v65
	v_max_f32_e32 v105, 0x358637bd, v67
	v_max_f32_e32 v100, 0x358637bd, v69
	v_max_f32_e32 v101, 0x358637bd, v71
	v_lshlrev_b32_e32 v65, 16, v96
	v_and_b32_e32 v67, 0xffff0000, v96
	v_lshlrev_b32_e32 v69, 16, v97
	v_and_b32_e32 v71, 0xffff0000, v97
	v_mul_f32_e32 v65, 0xbfb8aa3b, v65
	v_mul_f32_e32 v67, 0xbfb8aa3b, v67
	v_mul_f32_e32 v69, 0xbfb8aa3b, v69
	v_mul_f32_e32 v71, 0xbfb8aa3b, v71
	v_exp_f32_e32 v65, v65
	v_exp_f32_e32 v67, v67
	v_exp_f32_e32 v69, v69
	v_exp_f32_e32 v71, v71
	v_add_f32_e32 v65, 1.0, v65
	v_add_f32_e32 v67, 1.0, v67
	v_add_f32_e32 v69, 1.0, v69
	v_add_f32_e32 v71, 1.0, v71
	v_rcp_f32_e32 v65, v65
	v_rcp_f32_e32 v67, v67
	v_rcp_f32_e32 v69, v69
	v_rcp_f32_e32 v71, v71
	v_max_f32_e32 v98, 0x358637bd, v65
	v_max_f32_e32 v99, 0x358637bd, v67
	v_max_f32_e32 v96, 0x358637bd, v69
	v_max_f32_e32 v97, 0x358637bd, v71
	s_branch .LBB0_111

.LBB0_150:
	s_and_b64 vcc, exec, s[0:1]
	s_cbranch_vccz .LBB0_537
	v_readlane_b32 s0, v247, 46
	s_cmp_gt_i32 s0, 1
	s_mov_b64 s[0:1], -1
	s_cbranch_scc0 .LBB0_330
	v_readlane_b32 s0, v247, 46
	s_cmp_gt_i32 s0, 2
	s_mov_b64 s[0:1], -1
	s_cbranch_scc0 .LBB0_164
	v_readlane_b32 s0, v249, 55
	v_readlane_b32 s1, v249, 56
	s_waitcnt vmcnt(0) lgkmcnt(0)
	v_mov_b32_e32 v0, v167
	s_andn2_b64 vcc, exec, s[0:1]
	s_cbranch_vccnz .LBB0_163
	v_and_b32_e32 v3, 15, v0
	v_lshrrev_b32_e32 v2, 4, v0
	v_lshlrev_b32_e32 v1, 4, v3
	v_lshlrev_b32_e32 v0, 3, v3
	v_lshl_add_u32 v0, v2, 7, v0
	v_lshlrev_b32_e32 v3, 11, v3
	v_lshl_add_u32 v2, v2, 2, v3
	s_ashr_i32 s39, s38, 31
	s_mov_b32 s20, s38
	v_readlane_b32 s0, v249, 0
.Lscan_item:
	s_lshr_b32 s12, s0, 6
	s_bfe_u32 s14, s0, 0x20004
	s_bfe_u32 s15, s0, 0x10003
	s_and_b32 s16, s0, 7
	s_cmp_lt_u32 s12, 16
	s_cbranch_scc0 .Lscan_lat
	s_lshl_b32 s17, s12, 3
	s_mul_i32 s18, s15, 7
	s_add_i32 s17, s17, s18
	s_branch .Lscan_setup
.Lscan_lat:
	s_add_i32 s17, s12, -16
	s_lshl_b32 s17, s17, 5
	s_add_i32 s17, s17, 0x80
	s_mul_i32 s18, s15, 31
	s_add_i32 s17, s17, s18
.Lscan_setup:
	s_lshl_b32 s17, s17, 2
	s_add_i32 s17, s17, s14
	s_lshl_b32 s17, s17, 1
	s_add_i32 s17, s17, s15
	s_cmp_eq_u32 s15, 0
	s_mov_b32 s18, 0xfffe0000
	s_cselect_b32 s8, 0x20000, s18
	s_cselect_b32 s9, 0, -1
	s_mov_b32 s18, 0xfffff800
	s_cselect_b32 s10, 0x800, s18
	s_cselect_b32 s11, 0, -1
	s_lshl_b32 s18, s17, 14
	s_lshl_b32 s19, s16, 11
	s_add_i32 s18, s18, s19
	v_readlane_b32 s2, v249, 10
	v_readlane_b32 s3, v249, 11
	v_readlane_b32 s6, v249, 51
	v_readlane_b32 s7, v249, 52
	s_add_u32 s2, s2, s18
	s_addc_u32 s3, s3, 0
	s_add_u32 s6, s6, s18
	s_addc_u32 s7, s7, 0
	s_lshl_b32 s18, s17, 8
	v_readlane_b32 s4, v249, 57
	v_readlane_b32 s5, v249, 58
	s_add_u32 s4, s4, s18
	s_addc_u32 s5, s5, 0
	s_cmp_lt_u32 s12, 16
	s_cbranch_scc0 .Lscan_lat2
	v_mov_b32_e32 v4, 0
	v_mov_b32_e32 v5, 0
	v_mov_b32_e32 v6, 0
	v_mov_b32_e32 v7, 0
	global_load_dwordx2 v[20:21], v0, s[2:3]
	global_load_dwordx4 v[36:39], v1, s[4:5]
	s_add_u32 s2, s2, s8
	s_addc_u32 s3, s3, s9
	s_add_u32 s4, s4, s10
	s_addc_u32 s5, s5, s11
	global_load_dwordx2 v[22:23], v0, s[2:3]
	global_load_dwordx4 v[40:43], v1, s[4:5]
	s_add_u32 s2, s2, s8
	s_addc_u32 s3, s3, s9
	s_add_u32 s4, s4, s10
	s_addc_u32 s5, s5, s11
	global_load_dwordx2 v[24:25], v0, s[2:3]
	global_load_dwordx4 v[44:47], v1, s[4:5]
	s_add_u32 s2, s2, s8
	s_addc_u32 s3, s3, s9
	s_add_u32 s4, s4, s10
	s_addc_u32 s5, s5, s11
	global_load_dwordx2 v[26:27], v0, s[2:3]
	global_load_dwordx4 v[48:51], v1, s[4:5]
	s_add_u32 s2, s2, s8
	s_addc_u32 s3, s3, s9
	s_add_u32 s4, s4, s10
	s_addc_u32 s5, s5, s11
	global_load_dwordx2 v[28:29], v0, s[2:3]
	global_load_dwordx4 v[52:55], v1, s[4:5]
	s_add_u32 s2, s2, s8
	s_addc_u32 s3, s3, s9
	s_add_u32 s4, s4, s10
	s_addc_u32 s5, s5, s11
	global_load_dwordx2 v[30:31], v0, s[2:3]
	global_load_dwordx4 v[56:59], v1, s[4:5]
	s_add_u32 s2, s2, s8
	s_addc_u32 s3, s3, s9
	s_add_u32 s4, s4, s10
	s_addc_u32 s5, s5, s11
	global_load_dwordx2 v[32:33], v0, s[2:3]
	global_load_dwordx4 v[60:63], v1, s[4:5]
	s_add_u32 s2, s2, s8
	s_addc_u32 s3, s3, s9
	s_add_u32 s4, s4, s10
	s_addc_u32 s5, s5, s11
	global_load_dwordx2 v[34:35], v0, s[2:3]
	global_load_dwordx4 v[64:67], v1, s[4:5]
	s_add_u32 s2, s2, s8
	s_addc_u32 s3, s3, s9
	s_add_u32 s4, s4, s10
	s_addc_u32 s5, s5, s11
	v_cvt_pk_bf16_f32 v16, v4, v5
	v_cvt_pk_bf16_f32 v17, v6, v7
	global_store_dwordx2 v0, v[16:17], s[6:7]
	s_add_u32 s6, s6, s8
	s_addc_u32 s7, s7, s9
	s_waitcnt vmcnt(15)
	v_lshlrev_b32_e32 v12, 16, v20
	v_and_b32_e32 v13, 0xffff0000, v20
	v_lshlrev_b32_e32 v14, 16, v21
	v_and_b32_e32 v15, 0xffff0000, v21
	v_pk_add_f32 v[8:9], v[4:5], v[12:13]
	v_pk_add_f32 v[10:11], v[6:7], v[14:15]
	v_pk_mul_f32 v[4:5], v[36:37], v[8:9]
	v_pk_mul_f32 v[6:7], v[38:39], v[10:11]
	v_cvt_pk_bf16_f32 v18, v4, v5
	v_cvt_pk_bf16_f32 v19, v6, v7
	global_store_dwordx2 v0, v[18:19], s[6:7]
	s_add_u32 s6, s6, s8
	s_addc_u32 s7, s7, s9
	s_waitcnt vmcnt(14)
	v_lshlrev_b32_e32 v12, 16, v22
	v_and_b32_e32 v13, 0xffff0000, v22
	v_lshlrev_b32_e32 v14, 16, v23
	v_and_b32_e32 v15, 0xffff0000, v23
	v_pk_add_f32 v[8:9], v[4:5], v[12:13]
	v_pk_add_f32 v[10:11], v[6:7], v[14:15]
	v_pk_mul_f32 v[4:5], v[40:41], v[8:9]
	v_pk_mul_f32 v[6:7], v[42:43], v[10:11]
	v_cvt_pk_bf16_f32 v16, v4, v5
	v_cvt_pk_bf16_f32 v17, v6, v7
	global_store_dwordx2 v0, v[16:17], s[6:7]
	s_add_u32 s6, s6, s8
	s_addc_u32 s7, s7, s9
	s_waitcnt vmcnt(13)
	v_lshlrev_b32_e32 v12, 16, v24
	v_and_b32_e32 v13, 0xffff0000, v24
	v_lshlrev_b32_e32 v14, 16, v25
	v_and_b32_e32 v15, 0xffff0000, v25
	v_pk_add_f32 v[8:9], v[4:5], v[12:13]
	v_pk_add_f32 v[10:11], v[6:7], v[14:15]
	v_pk_mul_f32 v[4:5], v[44:45], v[8:9]
	v_pk_mul_f32 v[6:7], v[46:47], v[10:11]
	v_cvt_pk_bf16_f32 v18, v4, v5
	v_cvt_pk_bf16_f32 v19, v6, v7
	global_store_dwordx2 v0, v[18:19], s[6:7]
	s_add_u32 s6, s6, s8
	s_addc_u32 s7, s7, s9
	s_waitcnt vmcnt(12)
	v_lshlrev_b32_e32 v12, 16, v26
	v_and_b32_e32 v13, 0xffff0000, v26
	v_lshlrev_b32_e32 v14, 16, v27
	v_and_b32_e32 v15, 0xffff0000, v27
	v_pk_add_f32 v[8:9], v[4:5], v[12:13]
	v_pk_add_f32 v[10:11], v[6:7], v[14:15]
	v_pk_mul_f32 v[4:5], v[48:49], v[8:9]
	v_pk_mul_f32 v[6:7], v[50:51], v[10:11]
	v_cvt_pk_bf16_f32 v16, v4, v5
	v_cvt_pk_bf16_f32 v17, v6, v7
	global_store_dwordx2 v0, v[16:17], s[6:7]
	s_add_u32 s6, s6, s8
	s_addc_u32 s7, s7, s9
	s_waitcnt vmcnt(11)
	v_lshlrev_b32_e32 v12, 16, v28
	v_and_b32_e32 v13, 0xffff0000, v28
	v_lshlrev_b32_e32 v14, 16, v29
	v_and_b32_e32 v15, 0xffff0000, v29
	v_pk_add_f32 v[8:9], v[4:5], v[12:13]
	v_pk_add_f32 v[10:11], v[6:7], v[14:15]
	v_pk_mul_f32 v[4:5], v[52:53], v[8:9]
	v_pk_mul_f32 v[6:7], v[54:55], v[10:11]
	v_cvt_pk_bf16_f32 v18, v4, v5
	v_cvt_pk_bf16_f32 v19, v6, v7
	global_store_dwordx2 v0, v[18:19], s[6:7]
	s_add_u32 s6, s6, s8
	s_addc_u32 s7, s7, s9
	s_waitcnt vmcnt(10)
	v_lshlrev_b32_e32 v12, 16, v30
	v_and_b32_e32 v13, 0xffff0000, v30
	v_lshlrev_b32_e32 v14, 16, v31
	v_and_b32_e32 v15, 0xffff0000, v31
	v_pk_add_f32 v[8:9], v[4:5], v[12:13]
	v_pk_add_f32 v[10:11], v[6:7], v[14:15]
	v_pk_mul_f32 v[4:5], v[56:57], v[8:9]
	v_pk_mul_f32 v[6:7], v[58:59], v[10:11]
	v_cvt_pk_bf16_f32 v16, v4, v5
	v_cvt_pk_bf16_f32 v17, v6, v7
	global_store_dwordx2 v0, v[16:17], s[6:7]
	s_add_u32 s6, s6, s8
	s_addc_u32 s7, s7, s9
	s_waitcnt vmcnt(9)
	v_lshlrev_b32_e32 v12, 16, v32
	v_and_b32_e32 v13, 0xffff0000, v32
	v_lshlrev_b32_e32 v14, 16, v33
	v_and_b32_e32 v15, 0xffff0000, v33
	v_pk_add_f32 v[8:9], v[4:5], v[12:13]
	v_pk_add_f32 v[10:11], v[6:7], v[14:15]
	v_pk_mul_f32 v[4:5], v[60:61], v[8:9]
	v_pk_mul_f32 v[6:7], v[62:63], v[10:11]
	v_cvt_pk_bf16_f32 v18, v4, v5
	v_cvt_pk_bf16_f32 v19, v6, v7
	global_store_dwordx2 v0, v[18:19], s[6:7]
	s_add_u32 s6, s6, s8
	s_addc_u32 s7, s7, s9
	s_waitcnt vmcnt(8)
	v_lshlrev_b32_e32 v12, 16, v34
	v_and_b32_e32 v13, 0xffff0000, v34
	v_lshlrev_b32_e32 v14, 16, v35
	v_and_b32_e32 v15, 0xffff0000, v35
	v_pk_add_f32 v[8:9], v[4:5], v[12:13]
	v_pk_add_f32 v[10:11], v[6:7], v[14:15]
	v_pk_mul_f32 v[4:5], v[64:65], v[8:9]
	v_pk_mul_f32 v[6:7], v[66:67], v[10:11]
	s_lshl_b32 s17, s12, 2
	s_add_i32 s17, s17, s20
	s_lshl_b32 s17, s17, 1
	s_add_i32 s17, s17, s15
	s_lshl_b32 s17, s17, 2
	s_add_i32 s17, s17, s14
	s_lshl_b32 s17, s17, 15
	s_lshl_b32 s18, s16, 6
	s_add_i32 s17, s17, s18
	v_readlane_b32 s18, v249, 59
	v_readlane_b32 s19, v249, 60
	s_add_u32 s18, s18, s17
	s_addc_u32 s19, s19, 0
	global_store_dword v2, v4, s[18:19]
	global_store_dword v2, v5, s[18:19] offset:512
	global_store_dword v2, v6, s[18:19] offset:1024
	global_store_dword v2, v7, s[18:19] offset:1536
	s_branch .Lscan_next
.Lscan_lat2:
	s_add_i32 s17, s12, -16
	s_lshl_b32 s17, s17, 2
	s_add_i32 s17, s17, s20
	s_lshl_b32 s17, s17, 1
	s_add_i32 s17, s17, s15
	s_lshl_b32 s17, s17, 2
	s_add_i32 s17, s17, s14
	s_lshl_b32 s17, s17, 15
	s_lshl_b32 s18, s16, 6
	s_add_i32 s17, s17, s18
	v_readlane_b32 s18, v249, 23
	v_readlane_b32 s19, v249, 24
	s_add_u32 s18, s18, s17
	s_addc_u32 s19, s19, 0
	global_load_dword v4, v2, s[18:19]
	global_load_dword v5, v2, s[18:19] offset:512
	global_load_dword v6, v2, s[18:19] offset:1024
	global_load_dword v7, v2, s[18:19] offset:1536
	global_load_dwordx2 v[20:21], v0, s[2:3]
	global_load_dwordx4 v[36:39], v1, s[4:5]
	s_add_u32 s2, s2, s8
	s_addc_u32 s3, s3, s9
	s_add_u32 s4, s4, s10
	s_addc_u32 s5, s5, s11
	global_load_dwordx2 v[22:23], v0, s[2:3]
	global_load_dwordx4 v[40:43], v1, s[4:5]
	s_add_u32 s2, s2, s8
	s_addc_u32 s3, s3, s9
	s_add_u32 s4, s4, s10
	s_addc_u32 s5, s5, s11
	global_load_dwordx2 v[24:25], v0, s[2:3]
	global_load_dwordx4 v[44:47], v1, s[4:5]
	s_add_u32 s2, s2, s8
	s_addc_u32 s3, s3, s9
	s_add_u32 s4, s4, s10
	s_addc_u32 s5, s5, s11
	global_load_dwordx2 v[26:27], v0, s[2:3]
	global_load_dwordx4 v[48:51], v1, s[4:5]
	s_add_u32 s2, s2, s8
	s_addc_u32 s3, s3, s9
	s_add_u32 s4, s4, s10
	s_addc_u32 s5, s5, s11
	global_load_dwordx2 v[28:29], v0, s[2:3]
	global_load_dwordx4 v[52:55], v1, s[4:5]
	s_add_u32 s2, s2, s8
	s_addc_u32 s3, s3, s9
	s_add_u32 s4, s4, s10
	s_addc_u32 s5, s5, s11
	global_load_dwordx2 v[30:31], v0, s[2:3]
	global_load_dwordx4 v[56:59], v1, s[4:5]
	s_add_u32 s2, s2, s8
	s_addc_u32 s3, s3, s9
	s_add_u32 s4, s4, s10
	s_addc_u32 s5, s5, s11
	global_load_dwordx2 v[32:33], v0, s[2:3]
	global_load_dwordx4 v[60:63], v1, s[4:5]
	s_add_u32 s2, s2, s8
	s_addc_u32 s3, s3, s9
	s_add_u32 s4, s4, s10
	s_addc_u32 s5, s5, s11
	global_load_dwordx2 v[34:35], v0, s[2:3]
	global_load_dwordx4 v[64:67], v1, s[4:5]
	s_add_u32 s2, s2, s8
	s_addc_u32 s3, s3, s9
	s_add_u32 s4, s4, s10
	s_addc_u32 s5, s5, s11
	s_waitcnt vmcnt(16)
	v_cvt_pk_bf16_f32 v16, v4, v5
	v_cvt_pk_bf16_f32 v17, v6, v7
	global_store_dwordx2 v0, v[16:17], s[6:7]
	s_add_u32 s6, s6, s8
	s_addc_u32 s7, s7, s9
	s_waitcnt vmcnt(15)
	v_lshlrev_b32_e32 v12, 16, v20
	v_and_b32_e32 v13, 0xffff0000, v20
	v_lshlrev_b32_e32 v14, 16, v21
	v_and_b32_e32 v15, 0xffff0000, v21
	v_pk_add_f32 v[8:9], v[4:5], v[12:13]
	v_pk_add_f32 v[10:11], v[6:7], v[14:15]
	v_pk_mul_f32 v[4:5], v[36:37], v[8:9]
	v_pk_mul_f32 v[6:7], v[38:39], v[10:11]
	global_load_dwordx2 v[20:21], v0, s[2:3]
	global_load_dwordx4 v[36:39], v1, s[4:5]
	s_add_u32 s2, s2, s8
	s_addc_u32 s3, s3, s9
	s_add_u32 s4, s4, s10
	s_addc_u32 s5, s5, s11
	v_cvt_pk_bf16_f32 v18, v4, v5
	v_cvt_pk_bf16_f32 v19, v6, v7
	global_store_dwordx2 v0, v[18:19], s[6:7]
	s_add_u32 s6, s6, s8
	s_addc_u32 s7, s7, s9
	s_waitcnt vmcnt(16)
	v_lshlrev_b32_e32 v12, 16, v22
	v_and_b32_e32 v13, 0xffff0000, v22
	v_lshlrev_b32_e32 v14, 16, v23
	v_and_b32_e32 v15, 0xffff0000, v23
	v_pk_add_f32 v[8:9], v[4:5], v[12:13]
	v_pk_add_f32 v[10:11], v[6:7], v[14:15]
	v_pk_mul_f32 v[4:5], v[40:41], v[8:9]
	v_pk_mul_f32 v[6:7], v[42:43], v[10:11]
	global_load_dwordx2 v[22:23], v0, s[2:3]
	global_load_dwordx4 v[40:43], v1, s[4:5]
	s_add_u32 s2, s2, s8
	s_addc_u32 s3, s3, s9
	s_add_u32 s4, s4, s10
	s_addc_u32 s5, s5, s11
	v_cvt_pk_bf16_f32 v16, v4, v5
	v_cvt_pk_bf16_f32 v17, v6, v7
	global_store_dwordx2 v0, v[16:17], s[6:7]
	s_add_u32 s6, s6, s8
	s_addc_u32 s7, s7, s9
	s_waitcnt vmcnt(17)
	v_lshlrev_b32_e32 v12, 16, v24
	v_and_b32_e32 v13, 0xffff0000, v24
	v_lshlrev_b32_e32 v14, 16, v25
	v_and_b32_e32 v15, 0xffff0000, v25
	v_pk_add_f32 v[8:9], v[4:5], v[12:13]
	v_pk_add_f32 v[10:11], v[6:7], v[14:15]
	v_pk_mul_f32 v[4:5], v[44:45], v[8:9]
	v_pk_mul_f32 v[6:7], v[46:47], v[10:11]
	global_load_dwordx2 v[24:25], v0, s[2:3]
	global_load_dwordx4 v[44:47], v1, s[4:5]
	s_add_u32 s2, s2, s8
	s_addc_u32 s3, s3, s9
	s_add_u32 s4, s4, s10
	s_addc_u32 s5, s5, s11
	v_cvt_pk_bf16_f32 v18, v4, v5
	v_cvt_pk_bf16_f32 v19, v6, v7
	global_store_dwordx2 v0, v[18:19], s[6:7]
	s_add_u32 s6, s6, s8
	s_addc_u32 s7, s7, s9
	s_waitcnt vmcnt(18)
	v_lshlrev_b32_e32 v12, 16, v26
	v_and_b32_e32 v13, 0xffff0000, v26
	v_lshlrev_b32_e32 v14, 16, v27
	v_and_b32_e32 v15, 0xffff0000, v27
	v_pk_add_f32 v[8:9], v[4:5], v[12:13]
	v_pk_add_f32 v[10:11], v[6:7], v[14:15]
	v_pk_mul_f32 v[4:5], v[48:49], v[8:9]
	v_pk_mul_f32 v[6:7], v[50:51], v[10:11]
	global_load_dwordx2 v[26:27], v0, s[2:3]
	global_load_dwordx4 v[48:51], v1, s[4:5]
	s_add_u32 s2, s2, s8
	s_addc_u32 s3, s3, s9
	s_add_u32 s4, s4, s10
	s_addc_u32 s5, s5, s11
	v_cvt_pk_bf16_f32 v16, v4, v5
	v_cvt_pk_bf16_f32 v17, v6, v7
	global_store_dwordx2 v0, v[16:17], s[6:7]
	s_add_u32 s6, s6, s8
	s_addc_u32 s7, s7, s9
	s_waitcnt vmcnt(19)
	v_lshlrev_b32_e32 v12, 16, v28
	v_and_b32_e32 v13, 0xffff0000, v28
	v_lshlrev_b32_e32 v14, 16, v29
	v_and_b32_e32 v15, 0xffff0000, v29
	v_pk_add_f32 v[8:9], v[4:5], v[12:13]
	v_pk_add_f32 v[10:11], v[6:7], v[14:15]
	v_pk_mul_f32 v[4:5], v[52:53], v[8:9]
	v_pk_mul_f32 v[6:7], v[54:55], v[10:11]
	global_load_dwordx2 v[28:29], v0, s[2:3]
	global_load_dwordx4 v[52:55], v1, s[4:5]
	s_add_u32 s2, s2, s8
	s_addc_u32 s3, s3, s9
	s_add_u32 s4, s4, s10
	s_addc_u32 s5, s5, s11
	v_cvt_pk_bf16_f32 v18, v4, v5
	v_cvt_pk_bf16_f32 v19, v6, v7
	global_store_dwordx2 v0, v[18:19], s[6:7]
	s_add_u32 s6, s6, s8
	s_addc_u32 s7, s7, s9
	s_waitcnt vmcnt(20)
	v_lshlrev_b32_e32 v12, 16, v30
	v_and_b32_e32 v13, 0xffff0000, v30
	v_lshlrev_b32_e32 v14, 16, v31
	v_and_b32_e32 v15, 0xffff0000, v31
	v_pk_add_f32 v[8:9], v[4:5], v[12:13]
	v_pk_add_f32 v[10:11], v[6:7], v[14:15]
	v_pk_mul_f32 v[4:5], v[56:57], v[8:9]
	v_pk_mul_f32 v[6:7], v[58:59], v[10:11]
	global_load_dwordx2 v[30:31], v0, s[2:3]
	global_load_dwordx4 v[56:59], v1, s[4:5]
	s_add_u32 s2, s2, s8
	s_addc_u32 s3, s3, s9
	s_add_u32 s4, s4, s10
	s_addc_u32 s5, s5, s11
	v_cvt_pk_bf16_f32 v16, v4, v5
	v_cvt_pk_bf16_f32 v17, v6, v7
	global_store_dwordx2 v0, v[16:17], s[6:7]
	s_add_u32 s6, s6, s8
	s_addc_u32 s7, s7, s9
	s_waitcnt vmcnt(21)
	v_lshlrev_b32_e32 v12, 16, v32
	v_and_b32_e32 v13, 0xffff0000, v32
	v_lshlrev_b32_e32 v14, 16, v33
	v_and_b32_e32 v15, 0xffff0000, v33
	v_pk_add_f32 v[8:9], v[4:5], v[12:13]
	v_pk_add_f32 v[10:11], v[6:7], v[14:15]
	v_pk_mul_f32 v[4:5], v[60:61], v[8:9]
	v_pk_mul_f32 v[6:7], v[62:63], v[10:11]
	global_load_dwordx2 v[32:33], v0, s[2:3]
	global_load_dwordx4 v[60:63], v1, s[4:5]
	s_add_u32 s2, s2, s8
	s_addc_u32 s3, s3, s9
	s_add_u32 s4, s4, s10
	s_addc_u32 s5, s5, s11
	v_cvt_pk_bf16_f32 v18, v4, v5
	v_cvt_pk_bf16_f32 v19, v6, v7
	global_store_dwordx2 v0, v[18:19], s[6:7]
	s_add_u32 s6, s6, s8
	s_addc_u32 s7, s7, s9
	s_waitcnt vmcnt(22)
	v_lshlrev_b32_e32 v12, 16, v34
	v_and_b32_e32 v13, 0xffff0000, v34
	v_lshlrev_b32_e32 v14, 16, v35
	v_and_b32_e32 v15, 0xffff0000, v35
	v_pk_add_f32 v[8:9], v[4:5], v[12:13]
	v_pk_add_f32 v[10:11], v[6:7], v[14:15]
	v_pk_mul_f32 v[4:5], v[64:65], v[8:9]
	v_pk_mul_f32 v[6:7], v[66:67], v[10:11]
	global_load_dwordx2 v[34:35], v0, s[2:3]
	global_load_dwordx4 v[64:67], v1, s[4:5]
	s_add_u32 s2, s2, s8
	s_addc_u32 s3, s3, s9
	s_add_u32 s4, s4, s10
	s_addc_u32 s5, s5, s11
	v_cvt_pk_bf16_f32 v16, v4, v5
	v_cvt_pk_bf16_f32 v17, v6, v7
	global_store_dwordx2 v0, v[16:17], s[6:7]
	s_add_u32 s6, s6, s8
	s_addc_u32 s7, s7, s9
	s_waitcnt vmcnt(22)
	v_lshlrev_b32_e32 v12, 16, v20
	v_and_b32_e32 v13, 0xffff0000, v20
	v_lshlrev_b32_e32 v14, 16, v21
	v_and_b32_e32 v15, 0xffff0000, v21
	v_pk_add_f32 v[8:9], v[4:5], v[12:13]
	v_pk_add_f32 v[10:11], v[6:7], v[14:15]
	v_pk_mul_f32 v[4:5], v[36:37], v[8:9]
	v_pk_mul_f32 v[6:7], v[38:39], v[10:11]
	global_load_dwordx2 v[20:21], v0, s[2:3]
	global_load_dwordx4 v[36:39], v1, s[4:5]
	s_add_u32 s2, s2, s8
	s_addc_u32 s3, s3, s9
	s_add_u32 s4, s4, s10
	s_addc_u32 s5, s5, s11
	v_cvt_pk_bf16_f32 v18, v4, v5
	v_cvt_pk_bf16_f32 v19, v6, v7
	global_store_dwordx2 v0, v[18:19], s[6:7]
	s_add_u32 s6, s6, s8
	s_addc_u32 s7, s7, s9
	s_waitcnt vmcnt(22)
	v_lshlrev_b32_e32 v12, 16, v22
	v_and_b32_e32 v13, 0xffff0000, v22
	v_lshlrev_b32_e32 v14, 16, v23
	v_and_b32_e32 v15, 0xffff0000, v23
	v_pk_add_f32 v[8:9], v[4:5], v[12:13]
	v_pk_add_f32 v[10:11], v[6:7], v[14:15]
	v_pk_mul_f32 v[4:5], v[40:41], v[8:9]
	v_pk_mul_f32 v[6:7], v[42:43], v[10:11]
	global_load_dwordx2 v[22:23], v0, s[2:3]
	global_load_dwordx4 v[40:43], v1, s[4:5]
	s_add_u32 s2, s2, s8
	s_addc_u32 s3, s3, s9
	s_add_u32 s4, s4, s10
	s_addc_u32 s5, s5, s11
	v_cvt_pk_bf16_f32 v16, v4, v5
	v_cvt_pk_bf16_f32 v17, v6, v7
	global_store_dwordx2 v0, v[16:17], s[6:7]
	s_add_u32 s6, s6, s8
	s_addc_u32 s7, s7, s9
	s_waitcnt vmcnt(22)
	v_lshlrev_b32_e32 v12, 16, v24
	v_and_b32_e32 v13, 0xffff0000, v24
	v_lshlrev_b32_e32 v14, 16, v25
	v_and_b32_e32 v15, 0xffff0000, v25
	v_pk_add_f32 v[8:9], v[4:5], v[12:13]
	v_pk_add_f32 v[10:11], v[6:7], v[14:15]
	v_pk_mul_f32 v[4:5], v[44:45], v[8:9]
	v_pk_mul_f32 v[6:7], v[46:47], v[10:11]
	global_load_dwordx2 v[24:25], v0, s[2:3]
	global_load_dwordx4 v[44:47], v1, s[4:5]
	s_add_u32 s2, s2, s8
	s_addc_u32 s3, s3, s9
	s_add_u32 s4, s4, s10
	s_addc_u32 s5, s5, s11
	v_cvt_pk_bf16_f32 v18, v4, v5
	v_cvt_pk_bf16_f32 v19, v6, v7
	global_store_dwordx2 v0, v[18:19], s[6:7]
	s_add_u32 s6, s6, s8
	s_addc_u32 s7, s7, s9
	s_waitcnt vmcnt(22)
	v_lshlrev_b32_e32 v12, 16, v26
	v_and_b32_e32 v13, 0xffff0000, v26
	v_lshlrev_b32_e32 v14, 16, v27
	v_and_b32_e32 v15, 0xffff0000, v27
	v_pk_add_f32 v[8:9], v[4:5], v[12:13]
	v_pk_add_f32 v[10:11], v[6:7], v[14:15]
	v_pk_mul_f32 v[4:5], v[48:49], v[8:9]
	v_pk_mul_f32 v[6:7], v[50:51], v[10:11]
	global_load_dwordx2 v[26:27], v0, s[2:3]
	global_load_dwordx4 v[48:51], v1, s[4:5]
	s_add_u32 s2, s2, s8
	s_addc_u32 s3, s3, s9
	s_add_u32 s4, s4, s10
	s_addc_u32 s5, s5, s11
	v_cvt_pk_bf16_f32 v16, v4, v5
	v_cvt_pk_bf16_f32 v17, v6, v7
	global_store_dwordx2 v0, v[16:17], s[6:7]
	s_add_u32 s6, s6, s8
	s_addc_u32 s7, s7, s9
	s_waitcnt vmcnt(22)
	v_lshlrev_b32_e32 v12, 16, v28
	v_and_b32_e32 v13, 0xffff0000, v28
	v_lshlrev_b32_e32 v14, 16, v29
	v_and_b32_e32 v15, 0xffff0000, v29
	v_pk_add_f32 v[8:9], v[4:5], v[12:13]
	v_pk_add_f32 v[10:11], v[6:7], v[14:15]
	v_pk_mul_f32 v[4:5], v[52:53], v[8:9]
	v_pk_mul_f32 v[6:7], v[54:55], v[10:11]
	global_load_dwordx2 v[28:29], v0, s[2:3]
	global_load_dwordx4 v[52:55], v1, s[4:5]
	s_add_u32 s2, s2, s8
	s_addc_u32 s3, s3, s9
	s_add_u32 s4, s4, s10
	s_addc_u32 s5, s5, s11
	v_cvt_pk_bf16_f32 v18, v4, v5
	v_cvt_pk_bf16_f32 v19, v6, v7
	global_store_dwordx2 v0, v[18:19], s[6:7]
	s_add_u32 s6, s6, s8
	s_addc_u32 s7, s7, s9
	s_waitcnt vmcnt(22)
	v_lshlrev_b32_e32 v12, 16, v30
	v_and_b32_e32 v13, 0xffff0000, v30
	v_lshlrev_b32_e32 v14, 16, v31
	v_and_b32_e32 v15, 0xffff0000, v31
	v_pk_add_f32 v[8:9], v[4:5], v[12:13]
	v_pk_add_f32 v[10:11], v[6:7], v[14:15]
	v_pk_mul_f32 v[4:5], v[56:57], v[8:9]
	v_pk_mul_f32 v[6:7], v[58:59], v[10:11]
	global_load_dwordx2 v[30:31], v0, s[2:3]
	global_load_dwordx4 v[56:59], v1, s[4:5]
	s_add_u32 s2, s2, s8
	s_addc_u32 s3, s3, s9
	s_add_u32 s4, s4, s10
	s_addc_u32 s5, s5, s11
	v_cvt_pk_bf16_f32 v16, v4, v5
	v_cvt_pk_bf16_f32 v17, v6, v7
	global_store_dwordx2 v0, v[16:17], s[6:7]
	s_add_u32 s6, s6, s8
	s_addc_u32 s7, s7, s9
	s_waitcnt vmcnt(22)
	v_lshlrev_b32_e32 v12, 16, v32
	v_and_b32_e32 v13, 0xffff0000, v32
	v_lshlrev_b32_e32 v14, 16, v33
	v_and_b32_e32 v15, 0xffff0000, v33
	v_pk_add_f32 v[8:9], v[4:5], v[12:13]
	v_pk_add_f32 v[10:11], v[6:7], v[14:15]
	v_pk_mul_f32 v[4:5], v[60:61], v[8:9]
	v_pk_mul_f32 v[6:7], v[62:63], v[10:11]
	global_load_dwordx2 v[32:33], v0, s[2:3]
	global_load_dwordx4 v[60:63], v1, s[4:5]
	s_add_u32 s2, s2, s8
	s_addc_u32 s3, s3, s9
	s_add_u32 s4, s4, s10
	s_addc_u32 s5, s5, s11
	v_cvt_pk_bf16_f32 v18, v4, v5
	v_cvt_pk_bf16_f32 v19, v6, v7
	global_store_dwordx2 v0, v[18:19], s[6:7]
	s_add_u32 s6, s6, s8
	s_addc_u32 s7, s7, s9
	s_waitcnt vmcnt(22)
	v_lshlrev_b32_e32 v12, 16, v34
	v_and_b32_e32 v13, 0xffff0000, v34
	v_lshlrev_b32_e32 v14, 16, v35
	v_and_b32_e32 v15, 0xffff0000, v35
	v_pk_add_f32 v[8:9], v[4:5], v[12:13]
	v_pk_add_f32 v[10:11], v[6:7], v[14:15]
	v_pk_mul_f32 v[4:5], v[64:65], v[8:9]
	v_pk_mul_f32 v[6:7], v[66:67], v[10:11]
	global_load_dwordx2 v[34:35], v0, s[2:3]
	global_load_dwordx4 v[64:67], v1, s[4:5]
	s_add_u32 s2, s2, s8
	s_addc_u32 s3, s3, s9
	s_add_u32 s4, s4, s10
	s_addc_u32 s5, s5, s11
	v_cvt_pk_bf16_f32 v16, v4, v5
	v_cvt_pk_bf16_f32 v17, v6, v7
	global_store_dwordx2 v0, v[16:17], s[6:7]
	s_add_u32 s6, s6, s8
	s_addc_u32 s7, s7, s9
	s_waitcnt vmcnt(22)
	v_lshlrev_b32_e32 v12, 16, v20
	v_and_b32_e32 v13, 0xffff0000, v20
	v_lshlrev_b32_e32 v14, 16, v21
	v_and_b32_e32 v15, 0xffff0000, v21
	v_pk_add_f32 v[8:9], v[4:5], v[12:13]
	v_pk_add_f32 v[10:11], v[6:7], v[14:15]
	v_pk_mul_f32 v[4:5], v[36:37], v[8:9]
	v_pk_mul_f32 v[6:7], v[38:39], v[10:11]
	global_load_dwordx2 v[20:21], v0, s[2:3]
	global_load_dwordx4 v[36:39], v1, s[4:5]
	s_add_u32 s2, s2, s8
	s_addc_u32 s3, s3, s9
	s_add_u32 s4, s4, s10
	s_addc_u32 s5, s5, s11
	v_cvt_pk_bf16_f32 v18, v4, v5
	v_cvt_pk_bf16_f32 v19, v6, v7
	global_store_dwordx2 v0, v[18:19], s[6:7]
	s_add_u32 s6, s6, s8
	s_addc_u32 s7, s7, s9
	s_waitcnt vmcnt(22)
	v_lshlrev_b32_e32 v12, 16, v22
	v_and_b32_e32 v13, 0xffff0000, v22
	v_lshlrev_b32_e32 v14, 16, v23
	v_and_b32_e32 v15, 0xffff0000, v23
	v_pk_add_f32 v[8:9], v[4:5], v[12:13]
	v_pk_add_f32 v[10:11], v[6:7], v[14:15]
	v_pk_mul_f32 v[4:5], v[40:41], v[8:9]
	v_pk_mul_f32 v[6:7], v[42:43], v[10:11]
	global_load_dwordx2 v[22:23], v0, s[2:3]
	global_load_dwordx4 v[40:43], v1, s[4:5]
	s_add_u32 s2, s2, s8
	s_addc_u32 s3, s3, s9
	s_add_u32 s4, s4, s10
	s_addc_u32 s5, s5, s11
	v_cvt_pk_bf16_f32 v16, v4, v5
	v_cvt_pk_bf16_f32 v17, v6, v7
	global_store_dwordx2 v0, v[16:17], s[6:7]
	s_add_u32 s6, s6, s8
	s_addc_u32 s7, s7, s9
	s_waitcnt vmcnt(22)
	v_lshlrev_b32_e32 v12, 16, v24
	v_and_b32_e32 v13, 0xffff0000, v24
	v_lshlrev_b32_e32 v14, 16, v25
	v_and_b32_e32 v15, 0xffff0000, v25
	v_pk_add_f32 v[8:9], v[4:5], v[12:13]
	v_pk_add_f32 v[10:11], v[6:7], v[14:15]
	v_pk_mul_f32 v[4:5], v[44:45], v[8:9]
	v_pk_mul_f32 v[6:7], v[46:47], v[10:11]
	global_load_dwordx2 v[24:25], v0, s[2:3]
	global_load_dwordx4 v[44:47], v1, s[4:5]
	s_add_u32 s2, s2, s8
	s_addc_u32 s3, s3, s9
	s_add_u32 s4, s4, s10
	s_addc_u32 s5, s5, s11
	v_cvt_pk_bf16_f32 v18, v4, v5
	v_cvt_pk_bf16_f32 v19, v6, v7
	global_store_dwordx2 v0, v[18:19], s[6:7]
	s_add_u32 s6, s6, s8
	s_addc_u32 s7, s7, s9
	s_waitcnt vmcnt(22)
	v_lshlrev_b32_e32 v12, 16, v26
	v_and_b32_e32 v13, 0xffff0000, v26
	v_lshlrev_b32_e32 v14, 16, v27
	v_and_b32_e32 v15, 0xffff0000, v27
	v_pk_add_f32 v[8:9], v[4:5], v[12:13]
	v_pk_add_f32 v[10:11], v[6:7], v[14:15]
	v_pk_mul_f32 v[4:5], v[48:49], v[8:9]
	v_pk_mul_f32 v[6:7], v[50:51], v[10:11]
	global_load_dwordx2 v[26:27], v0, s[2:3]
	global_load_dwordx4 v[48:51], v1, s[4:5]
	s_add_u32 s2, s2, s8
	s_addc_u32 s3, s3, s9
	s_add_u32 s4, s4, s10
	s_addc_u32 s5, s5, s11
	v_cvt_pk_bf16_f32 v16, v4, v5
	v_cvt_pk_bf16_f32 v17, v6, v7
	global_store_dwordx2 v0, v[16:17], s[6:7]
	s_add_u32 s6, s6, s8
	s_addc_u32 s7, s7, s9
	s_waitcnt vmcnt(22)
	v_lshlrev_b32_e32 v12, 16, v28
	v_and_b32_e32 v13, 0xffff0000, v28
	v_lshlrev_b32_e32 v14, 16, v29
	v_and_b32_e32 v15, 0xffff0000, v29
	v_pk_add_f32 v[8:9], v[4:5], v[12:13]
	v_pk_add_f32 v[10:11], v[6:7], v[14:15]
	v_pk_mul_f32 v[4:5], v[52:53], v[8:9]
	v_pk_mul_f32 v[6:7], v[54:55], v[10:11]
	global_load_dwordx2 v[28:29], v0, s[2:3]
	global_load_dwordx4 v[52:55], v1, s[4:5]
	s_add_u32 s2, s2, s8
	s_addc_u32 s3, s3, s9
	s_add_u32 s4, s4, s10
	s_addc_u32 s5, s5, s11
	v_cvt_pk_bf16_f32 v18, v4, v5
	v_cvt_pk_bf16_f32 v19, v6, v7
	global_store_dwordx2 v0, v[18:19], s[6:7]
	s_add_u32 s6, s6, s8
	s_addc_u32 s7, s7, s9
	s_waitcnt vmcnt(22)
	v_lshlrev_b32_e32 v12, 16, v30
	v_and_b32_e32 v13, 0xffff0000, v30
	v_lshlrev_b32_e32 v14, 16, v31
	v_and_b32_e32 v15, 0xffff0000, v31
	v_pk_add_f32 v[8:9], v[4:5], v[12:13]
	v_pk_add_f32 v[10:11], v[6:7], v[14:15]
	v_pk_mul_f32 v[4:5], v[56:57], v[8:9]
	v_pk_mul_f32 v[6:7], v[58:59], v[10:11]
	global_load_dwordx2 v[30:31], v0, s[2:3]
	global_load_dwordx4 v[56:59], v1, s[4:5]
	s_add_u32 s2, s2, s8
	s_addc_u32 s3, s3, s9
	s_add_u32 s4, s4, s10
	s_addc_u32 s5, s5, s11
	v_cvt_pk_bf16_f32 v16, v4, v5
	v_cvt_pk_bf16_f32 v17, v6, v7
	global_store_dwordx2 v0, v[16:17], s[6:7]
	s_add_u32 s6, s6, s8
	s_addc_u32 s7, s7, s9
	s_waitcnt vmcnt(22)
	v_lshlrev_b32_e32 v12, 16, v32
	v_and_b32_e32 v13, 0xffff0000, v32
	v_lshlrev_b32_e32 v14, 16, v33
	v_and_b32_e32 v15, 0xffff0000, v33
	v_pk_add_f32 v[8:9], v[4:5], v[12:13]
	v_pk_add_f32 v[10:11], v[6:7], v[14:15]
	v_pk_mul_f32 v[4:5], v[60:61], v[8:9]
	v_pk_mul_f32 v[6:7], v[62:63], v[10:11]
	global_load_dwordx2 v[32:33], v0, s[2:3]
	global_load_dwordx4 v[60:63], v1, s[4:5]
	s_add_u32 s2, s2, s8
	s_addc_u32 s3, s3, s9
	s_add_u32 s4, s4, s10
	s_addc_u32 s5, s5, s11
	v_cvt_pk_bf16_f32 v18, v4, v5
	v_cvt_pk_bf16_f32 v19, v6, v7
	global_store_dwordx2 v0, v[18:19], s[6:7]
	s_add_u32 s6, s6, s8
	s_addc_u32 s7, s7, s9
	s_waitcnt vmcnt(22)
	v_lshlrev_b32_e32 v12, 16, v34
	v_and_b32_e32 v13, 0xffff0000, v34
	v_lshlrev_b32_e32 v14, 16, v35
	v_and_b32_e32 v15, 0xffff0000, v35
	v_pk_add_f32 v[8:9], v[4:5], v[12:13]
	v_pk_add_f32 v[10:11], v[6:7], v[14:15]
	v_pk_mul_f32 v[4:5], v[64:65], v[8:9]
	v_pk_mul_f32 v[6:7], v[66:67], v[10:11]
	global_load_dwordx2 v[34:35], v0, s[2:3]
	global_load_dwordx4 v[64:67], v1, s[4:5]
	s_add_u32 s2, s2, s8
	s_addc_u32 s3, s3, s9
	s_add_u32 s4, s4, s10
	s_addc_u32 s5, s5, s11
	v_cvt_pk_bf16_f32 v16, v4, v5
	v_cvt_pk_bf16_f32 v17, v6, v7
	global_store_dwordx2 v0, v[16:17], s[6:7]
	s_add_u32 s6, s6, s8
	s_addc_u32 s7, s7, s9
	s_waitcnt vmcnt(22)
	v_lshlrev_b32_e32 v12, 16, v20
	v_and_b32_e32 v13, 0xffff0000, v20
	v_lshlrev_b32_e32 v14, 16, v21
	v_and_b32_e32 v15, 0xffff0000, v21
	v_pk_add_f32 v[8:9], v[4:5], v[12:13]
	v_pk_add_f32 v[10:11], v[6:7], v[14:15]
	v_pk_mul_f32 v[4:5], v[36:37], v[8:9]
	v_pk_mul_f32 v[6:7], v[38:39], v[10:11]
	v_cvt_pk_bf16_f32 v18, v4, v5
	v_cvt_pk_bf16_f32 v19, v6, v7
	global_store_dwordx2 v0, v[18:19], s[6:7]
	s_add_u32 s6, s6, s8
	s_addc_u32 s7, s7, s9
	s_waitcnt vmcnt(20)
	v_lshlrev_b32_e32 v12, 16, v22
	v_and_b32_e32 v13, 0xffff0000, v22
	v_lshlrev_b32_e32 v14, 16, v23
	v_and_b32_e32 v15, 0xffff0000, v23
	v_pk_add_f32 v[8:9], v[4:5], v[12:13]
	v_pk_add_f32 v[10:11], v[6:7], v[14:15]
	v_pk_mul_f32 v[4:5], v[40:41], v[8:9]
	v_pk_mul_f32 v[6:7], v[42:43], v[10:11]
	v_cvt_pk_bf16_f32 v16, v4, v5
	v_cvt_pk_bf16_f32 v17, v6, v7
	global_store_dwordx2 v0, v[16:17], s[6:7]
	s_add_u32 s6, s6, s8
	s_addc_u32 s7, s7, s9
	s_waitcnt vmcnt(18)
	v_lshlrev_b32_e32 v12, 16, v24
	v_and_b32_e32 v13, 0xffff0000, v24
	v_lshlrev_b32_e32 v14, 16, v25
	v_and_b32_e32 v15, 0xffff0000, v25
	v_pk_add_f32 v[8:9], v[4:5], v[12:13]
	v_pk_add_f32 v[10:11], v[6:7], v[14:15]
	v_pk_mul_f32 v[4:5], v[44:45], v[8:9]
	v_pk_mul_f32 v[6:7], v[46:47], v[10:11]
	v_cvt_pk_bf16_f32 v18, v4, v5
	v_cvt_pk_bf16_f32 v19, v6, v7
	global_store_dwordx2 v0, v[18:19], s[6:7]
	s_add_u32 s6, s6, s8
	s_addc_u32 s7, s7, s9
	s_waitcnt vmcnt(16)
	v_lshlrev_b32_e32 v12, 16, v26
	v_and_b32_e32 v13, 0xffff0000, v26
	v_lshlrev_b32_e32 v14, 16, v27
	v_and_b32_e32 v15, 0xffff0000, v27
	v_pk_add_f32 v[8:9], v[4:5], v[12:13]
	v_pk_add_f32 v[10:11], v[6:7], v[14:15]
	v_pk_mul_f32 v[4:5], v[48:49], v[8:9]
	v_pk_mul_f32 v[6:7], v[50:51], v[10:11]
	v_cvt_pk_bf16_f32 v16, v4, v5
	v_cvt_pk_bf16_f32 v17, v6, v7
	global_store_dwordx2 v0, v[16:17], s[6:7]
	s_add_u32 s6, s6, s8
	s_addc_u32 s7, s7, s9
	s_waitcnt vmcnt(14)
	v_lshlrev_b32_e32 v12, 16, v28
	v_and_b32_e32 v13, 0xffff0000, v28
	v_lshlrev_b32_e32 v14, 16, v29
	v_and_b32_e32 v15, 0xffff0000, v29
	v_pk_add_f32 v[8:9], v[4:5], v[12:13]
	v_pk_add_f32 v[10:11], v[6:7], v[14:15]
	v_pk_mul_f32 v[4:5], v[52:53], v[8:9]
	v_pk_mul_f32 v[6:7], v[54:55], v[10:11]
	v_cvt_pk_bf16_f32 v18, v4, v5
	v_cvt_pk_bf16_f32 v19, v6, v7
	global_store_dwordx2 v0, v[18:19], s[6:7]
	s_add_u32 s6, s6, s8
	s_addc_u32 s7, s7, s9
	s_waitcnt vmcnt(12)
	v_lshlrev_b32_e32 v12, 16, v30
	v_and_b32_e32 v13, 0xffff0000, v30
	v_lshlrev_b32_e32 v14, 16, v31
	v_and_b32_e32 v15, 0xffff0000, v31
	v_pk_add_f32 v[8:9], v[4:5], v[12:13]
	v_pk_add_f32 v[10:11], v[6:7], v[14:15]
	v_pk_mul_f32 v[4:5], v[56:57], v[8:9]
	v_pk_mul_f32 v[6:7], v[58:59], v[10:11]
	v_cvt_pk_bf16_f32 v16, v4, v5
	v_cvt_pk_bf16_f32 v17, v6, v7
	global_store_dwordx2 v0, v[16:17], s[6:7]
	s_add_u32 s6, s6, s8
	s_addc_u32 s7, s7, s9
	s_waitcnt vmcnt(10)
	v_lshlrev_b32_e32 v12, 16, v32
	v_and_b32_e32 v13, 0xffff0000, v32
	v_lshlrev_b32_e32 v14, 16, v33
	v_and_b32_e32 v15, 0xffff0000, v33
	v_pk_add_f32 v[8:9], v[4:5], v[12:13]
	v_pk_add_f32 v[10:11], v[6:7], v[14:15]
	v_pk_mul_f32 v[4:5], v[60:61], v[8:9]
	v_pk_mul_f32 v[6:7], v[62:63], v[10:11]
	v_cvt_pk_bf16_f32 v18, v4, v5
	v_cvt_pk_bf16_f32 v19, v6, v7
	global_store_dwordx2 v0, v[18:19], s[6:7]
	s_add_u32 s6, s6, s8
	s_addc_u32 s7, s7, s9
	s_waitcnt vmcnt(8)
	v_lshlrev_b32_e32 v12, 16, v34
	v_and_b32_e32 v13, 0xffff0000, v34
	v_lshlrev_b32_e32 v14, 16, v35
	v_and_b32_e32 v15, 0xffff0000, v35
	v_pk_add_f32 v[8:9], v[4:5], v[12:13]
	v_pk_add_f32 v[10:11], v[6:7], v[14:15]
	v_pk_mul_f32 v[4:5], v[64:65], v[8:9]
	v_pk_mul_f32 v[6:7], v[66:67], v[10:11]
.Lscan_next:
	v_readlane_b32 s14, v249, 7
	v_readlane_b32 s15, v249, 8
	s_load_dword s1, s[14:15], 0x0
	s_waitcnt lgkmcnt(0)
	s_add_i32 s0, s0, s1
	s_cmpk_lt_i32 s0, 0x480
	s_cbranch_scc1 .Lscan_item
	s_mov_b32 s38, s20
